# MLA attention loop: same wave-half ping-pong as the GQA loop (waves 0-3 rendezvous after softmax, waves 4-7 after QK; DMA per block = K(t+2), V(t+1))
# speedup vs baseline: 1.0154x; 1.0070x over previous
.LBB0_119:
	s_mov_b32 s38, s10
	s_ashr_i32 s9, s8, 31
	s_lshl_b32 s11, s20, 9
	s_add_u32 s12, s14, s11
	s_addc_u32 s13, s15, 0
	s_ashr_i32 s11, s10, 31
	v_lshl_add_u64 v[2:3], s[10:11], 0, v[170:171]
	v_lshl_add_u64 v[6:7], v[174:175], 0, s[10:11]
	v_lshlrev_b64 v[22:23], 12, v[2:3]
	v_lshlrev_b64 v[6:7], 12, v[6:7]
	v_lshl_add_u64 v[10:11], s[10:11], 0, v[172:173]
	v_lshl_add_u64 v[2:3], s[12:13], 0, v[22:23]
	v_mov_b32_e32 v189, v1
	v_lshl_add_u64 v[6:7], s[12:13], 0, v[6:7]
	v_lshlrev_b64 v[24:25], 12, v[10:11]
	v_lshl_add_u64 v[14:15], v[2:3], 0, v[188:189]
	v_lshl_add_u64 v[18:19], v[6:7], 0, v[188:189]
	v_lshl_add_u64 v[10:11], v[176:177], 0, v[24:25]
	global_load_dwordx4 v[2:5], v[14:15], off
	global_load_dwordx4 v[6:9], v[18:19], off
	s_nop 0
	global_load_dwordx4 v[10:13], v[10:11], off
	s_nop 0
	global_load_dwordx4 v[14:17], v[14:15], off offset:256
	s_nop 0
	global_load_dwordx4 v[18:21], v[18:19], off offset:256
	v_add_u32_e32 v26, 16, v198
	s_waitcnt vmcnt(0)
	s_and_b32 s22, s18, 7
	v_lshl_or_b32 v22, s22, 9, v22
	s_lshl_b32 s10, s21, 18
	v_lshl_add_u64 v[192:193], v[184:185], 0, v[24:25]
	v_lshl_add_u64 v[194:195], v[186:187], 0, v[22:23]
	s_add_u32 s21, s10, 0x40000
	s_mov_b32 s22, 0
	v_mov_b32_e32 v234, 0
	v_mov_b32_e32 v189, 0xf149f2ca
	s_mov_b64 s[10:11], 0
	s_waitcnt vmcnt(0)
	ds_write_b128 v26, v[14:17]
	v_add_u32_e32 v14, 16, v199
	s_waitcnt vmcnt(0)
	ds_write_b128 v14, v[18:21]
	v_add_u32_e32 v14, 16, v200
	ds_write_b128 v14, v[2:5] offset:32768
	ds_write_b128 v14, v[6:9] offset:45056
	v_add_u32_e32 v2, 16, v201
	v_mov_b32_e32 v16, v1
	v_mov_b32_e32 v17, v1
	ds_write_b128 v2, v[10:13] offset:32768
	v_mov_b32_e32 v2, v1
	v_mov_b32_e32 v3, v1
	v_mov_b32_e32 v4, v1
	v_mov_b32_e32 v5, v1
	v_mov_b32_e32 v6, v1
	v_mov_b32_e32 v7, v1
	v_mov_b32_e32 v8, v1
	v_mov_b32_e32 v9, v1
	v_mov_b32_e32 v10, v1
	v_mov_b32_e32 v11, v1
	v_mov_b32_e32 v12, v1
	v_mov_b32_e32 v13, v1
	v_mov_b32_e32 v14, v1
	v_mov_b32_e32 v15, v1
	v_mov_b64_e32 v[32:33], v[16:17]
	v_mov_b64_e32 v[48:49], v[16:17]
	v_mov_b64_e32 v[64:65], v[16:17]
	v_mov_b64_e32 v[30:31], v[14:15]
	v_mov_b64_e32 v[28:29], v[12:13]
	v_mov_b64_e32 v[26:27], v[10:11]
	v_mov_b64_e32 v[24:25], v[8:9]
	v_mov_b64_e32 v[22:23], v[6:7]
	v_mov_b64_e32 v[20:21], v[4:5]
	v_mov_b64_e32 v[18:19], v[2:3]
	v_mov_b64_e32 v[46:47], v[14:15]
	v_mov_b64_e32 v[44:45], v[12:13]
	v_mov_b64_e32 v[42:43], v[10:11]
	v_mov_b64_e32 v[40:41], v[8:9]
	v_mov_b64_e32 v[38:39], v[6:7]
	v_mov_b64_e32 v[36:37], v[4:5]
	v_mov_b64_e32 v[34:35], v[2:3]
	v_mov_b64_e32 v[62:63], v[14:15]
	v_mov_b64_e32 v[60:61], v[12:13]
	v_mov_b64_e32 v[58:59], v[10:11]
	v_mov_b64_e32 v[56:57], v[8:9]
	v_mov_b64_e32 v[54:55], v[6:7]
	v_mov_b64_e32 v[52:53], v[4:5]
	v_mov_b64_e32 v[50:51], v[2:3]
	s_waitcnt lgkmcnt(0)
	s_barrier
	s_lshl_b32 s12, s20, 9
	s_add_i32 s12, s12, 0x8400000
	v_and_b32_e32 v66, 63, v178
	v_lshrrev_b32_e32 v67, 6, v178
	v_mul_u32_u24_e32 v68, 0xc0, v67
	v_add_u32_e32 v68, v68, v66
	v_mul_u32_u24_e32 v70, 0xaab, v68
	v_lshrrev_b32_e32 v70, 16, v70
	v_mul_u32_u24_e32 v71, 24, v70
	v_sub_u32_e32 v71, v68, v71
	v_and_b32_e32 v72, 15, v70
	v_xor_b32_e32 v72, v71, v72
	v_lshlrev_b32_e32 v72, 4, v72
	v_add_u32_e32 v72, s12, v72
	v_add_u32_e32 v73, -16, v71
	v_and_b32_e32 v74, 7, v70
	v_xor_b32_e32 v73, v73, v74
	v_lshlrev_b32_e32 v73, 4, v73
	v_add_u32_e32 v73, 0x600, v73
	v_cmp_gt_u32_e32 vcc, 16, v71
	s_nop 1
	v_cndmask_b32_e32 v72, v73, v72, vcc
	v_lshl_add_u32 v247, v70, 12, v72
	v_add_u32_e32 v68, 64, v68
	v_mul_u32_u24_e32 v70, 0xaab, v68
	v_lshrrev_b32_e32 v70, 16, v70
	v_mul_u32_u24_e32 v71, 24, v70
	v_sub_u32_e32 v71, v68, v71
	v_and_b32_e32 v72, 15, v70
	v_xor_b32_e32 v72, v71, v72
	v_lshlrev_b32_e32 v72, 4, v72
	v_add_u32_e32 v72, s12, v72
	v_add_u32_e32 v73, -16, v71
	v_and_b32_e32 v74, 7, v70
	v_xor_b32_e32 v73, v73, v74
	v_lshlrev_b32_e32 v73, 4, v73
	v_add_u32_e32 v73, 0x600, v73
	v_cmp_gt_u32_e32 vcc, 16, v71
	s_nop 1
	v_cndmask_b32_e32 v72, v73, v72, vcc
	v_lshl_add_u32 v248, v70, 12, v72
	v_add_u32_e32 v68, 64, v68
	v_mul_u32_u24_e32 v70, 0xaab, v68
	v_lshrrev_b32_e32 v70, 16, v70
	v_mul_u32_u24_e32 v71, 24, v70
	v_sub_u32_e32 v71, v68, v71
	v_and_b32_e32 v72, 15, v70
	v_xor_b32_e32 v72, v71, v72
	v_lshlrev_b32_e32 v72, 4, v72
	v_add_u32_e32 v72, s12, v72
	v_add_u32_e32 v73, -16, v71
	v_and_b32_e32 v74, 7, v70
	v_xor_b32_e32 v73, v73, v74
	v_lshlrev_b32_e32 v73, 4, v73
	v_add_u32_e32 v73, 0x600, v73
	v_cmp_gt_u32_e32 vcc, 16, v71
	s_nop 1
	v_cndmask_b32_e32 v72, v73, v72, vcc
	v_lshl_add_u32 v249, v70, 12, v72
	v_and_b32_e32 v70, 31, v66
	v_lshrrev_b32_e32 v70, 2, v70
	v_lshl_add_u32 v70, v67, 3, v70
	v_lshrrev_b32_e32 v71, 5, v66
	v_lshlrev_b32_e32 v71, 6, v71
	v_and_b32_e32 v72, 3, v66
	v_lshlrev_b32_e32 v72, 4, v72
	v_add3_u32 v71, v71, v72, s12
	v_add_u32_e32 v71, 0x100, v71
	v_lshl_add_u32 v250, v70, 12, v71
	v_add_u32_e32 v251, 0x80, v250
	s_add_i32 s24, s38, 64
	s_lshl_b32 s24, s24, 12
	s_add_u32 s24, s24, 0x4600000
	s_add_u32 s24, s98, s24
	s_addc_u32 s25, s99, 0
	v_readlane_b32 s26, v254, 10
	s_nop 3
	s_lshr_b32 s36, s26, 6
	s_lshl_b32 s26, s26, 5
	s_add_i32 s26, s26, 16
	s_mul_i32 s36, s36, 0xc00
	s_add_i32 s36, s36, 0x8010
	s_movk_i32 s12, 0x2000
	v_add3_u32 v146, v203, v220, s12
	v_add3_u32 v147, v203, v221, s12
	v_add3_u32 v163, v203, v222, s12
	v_add3_u32 v164, v203, v223, s12
	v_add3_u32 v165, v203, v224, s12
	v_add3_u32 v156, v203, v225, s12
	v_add3_u32 v157, v203, v226, s12
	v_add3_u32 v158, v203, v227, s12
	v_add3_u32 v159, v203, v228, s12
	v_add3_u32 v160, v203, v229, s12
	v_add3_u32 v161, v203, v230, s12
	v_add3_u32 v162, v203, v231, s12
	s_mov_b32 s30, 0x13572468
	s_mov_b32 s30, 0x13572468
	s_mov_b32 s30, 0x13572468
	s_mov_b32 s30, 0x13572468
	s_mov_b32 s30, 0x13572468
	s_mov_b32 s30, 0x13572468
	s_mov_b32 s30, 0x13572468
	s_add_i32 m0, s36, 0x6000
	s_nop 0
	global_load_lds_dwordx4 v247, s[24:25]
	s_add_i32 m0, s36, 0x6400
	s_nop 0
	global_load_lds_dwordx4 v248, s[24:25]
	s_add_i32 m0, s36, 0x6800
	s_nop 0
	global_load_lds_dwordx4 v249, s[24:25]
	s_add_u32 s24, s24, 0x40000
	s_addc_u32 s25, s25, 0
	s_branch .Lmu_b120
.Lmu_a120:
	ds_read_b128 v[66:69], v146 offset:49152
	ds_read_b128 v[70:73], v146 offset:61440
	ds_read_b128 v[236:239], v147 offset:49152
	ds_read_b128 v[240:243], v147 offset:61440
	s_waitcnt lgkmcnt(3)
	v_mfma_f32_32x32x16_bf16 v[82:97], v[66:69], v[134:137], 0
	s_waitcnt lgkmcnt(2)
	v_mfma_f32_32x32x16_bf16 v[66:81], v[70:73], v[134:137], 0
	ds_read_b128 v[148:151], v163 offset:49152
	ds_read_b128 v[152:155], v163 offset:61440
	s_waitcnt lgkmcnt(3)
	v_mfma_f32_32x32x16_bf16 v[82:97], v[236:239], v[130:133], v[82:97]
	s_waitcnt lgkmcnt(2)
	v_mfma_f32_32x32x16_bf16 v[66:81], v[240:243], v[130:133], v[66:81]
	ds_read_b128 v[236:239], v164 offset:49152
	ds_read_b128 v[240:243], v164 offset:61440
	s_waitcnt lgkmcnt(3)
	v_mfma_f32_32x32x16_bf16 v[82:97], v[148:151], v[126:129], v[82:97]
	s_waitcnt lgkmcnt(2)
	v_mfma_f32_32x32x16_bf16 v[66:81], v[152:155], v[126:129], v[66:81]
	ds_read_b128 v[148:151], v165 offset:49152
	ds_read_b128 v[152:155], v165 offset:61440
	s_waitcnt lgkmcnt(3)
	v_mfma_f32_32x32x16_bf16 v[82:97], v[236:239], v[122:125], v[82:97]
	s_waitcnt lgkmcnt(2)
	v_mfma_f32_32x32x16_bf16 v[66:81], v[240:243], v[122:125], v[66:81]
	ds_read_b128 v[236:239], v156 offset:49152
	ds_read_b128 v[240:243], v156 offset:61440
	s_waitcnt lgkmcnt(3)
	v_mfma_f32_32x32x16_bf16 v[82:97], v[148:151], v[118:121], v[82:97]
	s_waitcnt lgkmcnt(2)
	v_mfma_f32_32x32x16_bf16 v[66:81], v[152:155], v[118:121], v[66:81]
	ds_read_b128 v[148:151], v157 offset:49152
	ds_read_b128 v[152:155], v157 offset:61440
	s_waitcnt lgkmcnt(3)
	v_mfma_f32_32x32x16_bf16 v[82:97], v[236:239], v[114:117], v[82:97]
	s_waitcnt lgkmcnt(2)
	v_mfma_f32_32x32x16_bf16 v[66:81], v[240:243], v[114:117], v[66:81]
	ds_read_b128 v[236:239], v158 offset:49152
	ds_read_b128 v[240:243], v158 offset:61440
	s_waitcnt lgkmcnt(3)
	v_mfma_f32_32x32x16_bf16 v[82:97], v[148:151], v[110:113], v[82:97]
	s_waitcnt lgkmcnt(2)
	v_mfma_f32_32x32x16_bf16 v[66:81], v[152:155], v[110:113], v[66:81]
	ds_read_b128 v[148:151], v159 offset:49152
	ds_read_b128 v[152:155], v159 offset:61440
	s_waitcnt lgkmcnt(3)
	v_mfma_f32_32x32x16_bf16 v[82:97], v[236:239], v[106:109], v[82:97]
	s_waitcnt lgkmcnt(2)
	v_mfma_f32_32x32x16_bf16 v[66:81], v[240:243], v[106:109], v[66:81]
	ds_read_b128 v[236:239], v160 offset:49152
	ds_read_b128 v[240:243], v160 offset:61440
	s_waitcnt lgkmcnt(3)
	v_mfma_f32_32x32x16_bf16 v[82:97], v[148:151], v[102:105], v[82:97]
	s_waitcnt lgkmcnt(2)
	v_mfma_f32_32x32x16_bf16 v[66:81], v[152:155], v[102:105], v[66:81]
	ds_read_b128 v[148:151], v161 offset:49152
	ds_read_b128 v[152:155], v161 offset:61440
	s_waitcnt lgkmcnt(3)
	v_mfma_f32_32x32x16_bf16 v[82:97], v[236:239], v[98:101], v[82:97]
	s_waitcnt lgkmcnt(2)
	v_mfma_f32_32x32x16_bf16 v[66:81], v[240:243], v[98:101], v[66:81]
	ds_read_b128 v[236:239], v162 offset:49152
	ds_read_b128 v[240:243], v162 offset:61440
	s_waitcnt lgkmcnt(3)
	v_mfma_f32_32x32x16_bf16 v[82:97], v[148:151], v[138:141], v[82:97]
	s_waitcnt lgkmcnt(2)
	v_mfma_f32_32x32x16_bf16 v[66:81], v[152:155], v[138:141], v[66:81]
	s_waitcnt lgkmcnt(1)
	v_mfma_f32_32x32x16_bf16 v[82:97], v[236:239], v[142:145], v[82:97]
	s_waitcnt lgkmcnt(0)
	v_mfma_f32_32x32x16_bf16 v[66:81], v[240:243], v[142:145], v[66:81]
	s_cmpk_ge_u32 s26, 0x2010
	s_cbranch_scc0 .Lmpp_a_sA
	s_waitcnt vmcnt(0)
	s_barrier
	s_mov_b32 s30, 0x13572468
	s_sub_u32 s28, s24, 0x40000
	s_subb_u32 s29, s25, 0
	s_add_i32 m0, s26, 0x0
	s_nop 0
	global_load_lds_dwordx4 v250, s[28:29]
	s_add_i32 m0, s26, 0x400
	s_nop 0
	global_load_lds_dwordx4 v251, s[28:29]
	s_add_u32 s30, s10, 0x40000
	s_cmp_eq_u32 s30, s21
	s_cbranch_scc1 .Lmpp_a_s_nok
	s_add_i32 m0, s36, 0x6000
	s_nop 0
	global_load_lds_dwordx4 v247, s[24:25]
	s_add_i32 m0, s36, 0x6400
	s_nop 0
	global_load_lds_dwordx4 v248, s[24:25]
	s_add_i32 m0, s36, 0x6800
	s_nop 0
	global_load_lds_dwordx4 v249, s[24:25]
	s_add_u32 s24, s24, 0x40000
	s_addc_u32 s25, s25, 0

.Lmpp_a_sJ:
	s_nop 1
	v_max_f32_e32 v191, v83, v83
	v_max_f32_e32 v235, v82, v82
	v_max_f32_e32 v191, v235, v191
	v_max3_f32 v191, v191, v84, v85
	v_max3_f32 v191, v191, v86, v87
	v_max3_f32 v191, v191, v88, v89
	v_max3_f32 v191, v191, v90, v91
	v_max3_f32 v191, v191, v92, v93
	v_max3_f32 v191, v191, v94, v95
	v_max3_f32 v191, v191, v96, v97
	v_max3_f32 v191, v191, v66, v67
	v_max3_f32 v191, v191, v68, v69
	v_max3_f32 v191, v191, v70, v71
	v_max3_f32 v191, v191, v72, v73
	v_max3_f32 v191, v191, v74, v75
	v_max3_f32 v191, v191, v76, v77
	v_max3_f32 v191, v191, v78, v79
	v_max3_f32 v191, v191, v80, v81
	v_mov_b32_e32 v235, v191
	s_nop 1
	v_permlane32_swap_b32_e32 v191, v235
	v_max_f32_e32 v235, v235, v235
	v_max_f32_e32 v191, v191, v191
	v_max_f32_e32 v191, v191, v235
	v_sub_f32_e32 v235, v191, v189
	v_cmp_ge_f32_e32 vcc, s56, v235
	s_cmp_eq_u64 vcc, exec
	v_max_f32_e32 v235, v189, v189
	s_cselect_b64 vcc, -1, 0
	v_max_f32_e32 v191, v235, v191
	v_sub_f32_e32 v235, v189, v191
	v_cndmask_b32_e32 v189, v191, v189, vcc
	v_mul_f32_e32 v191, 0xbdd53b94, v189
	v_fmamk_f32 v82, v82, 0x3dd53b94, v191
	v_fmamk_f32 v83, v83, 0x3dd53b94, v191
	v_fmamk_f32 v84, v84, 0x3dd53b94, v191
	v_fmamk_f32 v85, v85, 0x3dd53b94, v191
	v_fmamk_f32 v86, v86, 0x3dd53b94, v191
	v_fmamk_f32 v87, v87, 0x3dd53b94, v191
	v_fmamk_f32 v88, v88, 0x3dd53b94, v191
	v_fmamk_f32 v89, v89, 0x3dd53b94, v191
	v_fmamk_f32 v90, v90, 0x3dd53b94, v191
	v_fmamk_f32 v91, v91, 0x3dd53b94, v191
	v_fmamk_f32 v92, v92, 0x3dd53b94, v191
	v_fmamk_f32 v93, v93, 0x3dd53b94, v191
	v_fmamk_f32 v94, v94, 0x3dd53b94, v191
	v_fmamk_f32 v95, v95, 0x3dd53b94, v191
	v_fmamk_f32 v96, v96, 0x3dd53b94, v191
	v_fmamk_f32 v97, v97, 0x3dd53b94, v191
	v_fmamk_f32 v66, v66, 0x3dd53b94, v191
	v_fmamk_f32 v67, v67, 0x3dd53b94, v191
	v_fmamk_f32 v68, v68, 0x3dd53b94, v191
	v_fmamk_f32 v69, v69, 0x3dd53b94, v191
	v_fmamk_f32 v70, v70, 0x3dd53b94, v191
	v_fmamk_f32 v71, v71, 0x3dd53b94, v191
	v_fmamk_f32 v72, v72, 0x3dd53b94, v191
	v_fmamk_f32 v73, v73, 0x3dd53b94, v191
	v_fmamk_f32 v74, v74, 0x3dd53b94, v191
	v_fmamk_f32 v75, v75, 0x3dd53b94, v191
	v_fmamk_f32 v76, v76, 0x3dd53b94, v191
	v_fmamk_f32 v77, v77, 0x3dd53b94, v191
	v_fmamk_f32 v78, v78, 0x3dd53b94, v191
	v_fmamk_f32 v79, v79, 0x3dd53b94, v191
	v_fmamk_f32 v80, v80, 0x3dd53b94, v191
	v_fmac_f32_e32 v191, 0x3dd53b94, v81
	v_exp_f32_e32 v81, v82
	v_exp_f32_e32 v236, v83
	v_exp_f32_e32 v84, v84
	v_exp_f32_e32 v85, v85
	v_exp_f32_e32 v86, v86
	v_exp_f32_e32 v237, v70
	v_add_f32_e32 v70, 0, v81
	v_exp_f32_e32 v87, v87
	v_add_f32_e32 v70, v236, v70
	v_exp_f32_e32 v88, v88
	v_add_f32_e32 v70, v84, v70
	v_exp_f32_e32 v89, v89
	v_add_f32_e32 v70, v85, v70
	v_exp_f32_e32 v90, v90
	v_add_f32_e32 v70, v86, v70
	v_exp_f32_e32 v91, v91
	v_add_f32_e32 v70, v87, v70
	v_exp_f32_e32 v92, v92
	v_add_f32_e32 v70, v88, v70
	v_exp_f32_e32 v93, v93
	v_add_f32_e32 v70, v89, v70
	v_exp_f32_e32 v94, v94
	v_add_f32_e32 v70, v90, v70
	v_exp_f32_e32 v95, v95
	v_add_f32_e32 v70, v91, v70
	v_exp_f32_e32 v96, v96
	v_add_f32_e32 v70, v92, v70
	v_exp_f32_e32 v97, v97
	v_add_f32_e32 v70, v93, v70
	v_exp_f32_e32 v66, v66
	v_add_f32_e32 v70, v94, v70
	v_exp_f32_e32 v67, v67
	v_add_f32_e32 v70, v95, v70
	v_exp_f32_e32 v68, v68
	v_add_f32_e32 v70, v96, v70
	v_exp_f32_e32 v69, v69
	v_add_f32_e32 v70, v97, v70
	v_add_f32_e32 v70, v66, v70
	v_exp_f32_e32 v238, v71
	v_add_f32_e32 v70, v67, v70
	v_exp_f32_e32 v239, v72
	v_add_f32_e32 v70, v68, v70
	v_exp_f32_e32 v73, v73
	v_add_f32_e32 v70, v69, v70
	v_exp_f32_e32 v240, v74
	v_add_f32_e32 v70, v237, v70
	v_exp_f32_e32 v241, v75
	v_add_f32_e32 v70, v238, v70
	v_exp_f32_e32 v242, v76
	v_add_f32_e32 v70, v239, v70
	v_exp_f32_e32 v243, v77
	v_add_f32_e32 v70, v73, v70
	v_exp_f32_e32 v244, v78
	v_add_f32_e32 v70, v240, v70
	v_exp_f32_e32 v245, v79
	v_add_f32_e32 v70, v241, v70
	v_exp_f32_e32 v246, v80
	v_add_f32_e32 v70, v242, v70
	v_mul_f32_e32 v235, 0x3dd53b94, v235
	v_exp_f32_e32 v191, v191
	v_add_f32_e32 v70, v243, v70
	v_exp_f32_e32 v235, v235
	v_add_f32_e32 v70, v244, v70
	v_add_f32_e32 v70, v245, v70
	v_add_f32_e32 v70, v246, v70
	v_add_f32_e32 v82, v191, v70
	v_cndmask_b32_e64 v235, v235, 1.0, vcc
	v_mov_b32_e32 v83, v82
	s_nop 1
	v_permlane32_swap_b32_e32 v82, v83
	v_cmp_gt_f32_e32 vcc, 1.0, v235
	v_cvt_pk_bf16_f32 v78, v81, v236
	v_cvt_pk_bf16_f32 v79, v84, v85
	v_cvt_pk_bf16_f32 v80, v86, v87
	v_cvt_pk_bf16_f32 v81, v88, v89
	v_cvt_pk_bf16_f32 v74, v90, v91
	v_cvt_pk_bf16_f32 v75, v92, v93
	v_cvt_pk_bf16_f32 v76, v94, v95
	v_cvt_pk_bf16_f32 v77, v96, v97
	v_cvt_pk_bf16_f32 v70, v66, v67
	v_cvt_pk_bf16_f32 v71, v68, v69
	v_cvt_pk_bf16_f32 v72, v237, v238
	v_cvt_pk_bf16_f32 v73, v239, v73
	v_cvt_pk_bf16_f32 v66, v240, v241
	v_cvt_pk_bf16_f32 v67, v242, v243
	v_cvt_pk_bf16_f32 v68, v244, v245
	v_cvt_pk_bf16_f32 v69, v246, v191
	s_cbranch_vccz .Lmu_a124
	s_and_saveexec_b64 s[12:13], s[4:5]
	ds_write_b32 v232, v235 offset:128
	s_or_b64 exec, exec, s[12:13]
	s_waitcnt lgkmcnt(0)
	v_add_u32_e32 v96, v196, v202
	ds_read_b128 v[84:87], v96 offset:224
	ds_read_b128 v[88:91], v96 offset:192
	ds_read_b128 v[92:95], v96 offset:160
	ds_read_b128 v[236:239], v96 offset:128
	s_waitcnt lgkmcnt(3)
	v_pk_mul_f32 v[14:15], v[14:15], v[84:85]
	s_waitcnt lgkmcnt(2)
	v_pk_mul_f32 v[10:11], v[10:11], v[88:89]
	s_waitcnt lgkmcnt(1)
	v_pk_mul_f32 v[6:7], v[6:7], v[92:93]
	v_pk_mul_f32 v[16:17], v[16:17], v[86:87]
	v_pk_mul_f32 v[12:13], v[12:13], v[90:91]
	v_pk_mul_f32 v[8:9], v[8:9], v[94:95]
	s_waitcnt lgkmcnt(0)
	v_pk_mul_f32 v[4:5], v[4:5], v[238:239]
	v_pk_mul_f32 v[2:3], v[2:3], v[236:237]
	v_pk_mul_f32 v[30:31], v[30:31], v[84:85]
	v_pk_mul_f32 v[26:27], v[26:27], v[88:89]
	v_pk_mul_f32 v[22:23], v[22:23], v[92:93]
	v_pk_mul_f32 v[32:33], v[32:33], v[86:87]
	v_pk_mul_f32 v[28:29], v[28:29], v[90:91]
	v_pk_mul_f32 v[24:25], v[24:25], v[94:95]
	v_pk_mul_f32 v[20:21], v[20:21], v[238:239]
	v_pk_mul_f32 v[18:19], v[18:19], v[236:237]
	v_pk_mul_f32 v[46:47], v[46:47], v[84:85]
	v_pk_mul_f32 v[42:43], v[42:43], v[88:89]
	v_pk_mul_f32 v[38:39], v[38:39], v[92:93]
	v_pk_mul_f32 v[48:49], v[48:49], v[86:87]
	v_pk_mul_f32 v[44:45], v[44:45], v[90:91]
	v_pk_mul_f32 v[40:41], v[40:41], v[94:95]
	v_pk_mul_f32 v[36:37], v[36:37], v[238:239]
	v_pk_mul_f32 v[34:35], v[34:35], v[236:237]
	v_pk_mul_f32 v[62:63], v[62:63], v[84:85]
	v_pk_mul_f32 v[58:59], v[58:59], v[88:89]
	v_pk_mul_f32 v[54:55], v[54:55], v[92:93]
	v_pk_mul_f32 v[64:65], v[64:65], v[86:87]
	v_pk_mul_f32 v[60:61], v[60:61], v[90:91]
	v_pk_mul_f32 v[56:57], v[56:57], v[94:95]
	v_pk_mul_f32 v[52:53], v[52:53], v[238:239]
	v_pk_mul_f32 v[50:51], v[50:51], v[236:237]
.Lmu_a124:
	v_add_f32_e32 v191, v82, v83
	v_fmac_f32_e32 v191, v234, v235
	s_cmpk_ge_u32 s26, 0x2010
	s_cbranch_scc1 .Lmpp_a_pJ
	s_waitcnt vmcnt(0)
	s_barrier
	s_mov_b32 s30, 0x13572468
	s_mov_b32 s30, 0x13572468
	s_mov_b32 s30, 0x13572468
	s_mov_b32 s30, 0x13572468
	s_mov_b32 s30, 0x13572468
	s_mov_b32 s30, 0x13572468
	s_sub_u32 s28, s24, 0x40000
	s_subb_u32 s29, s25, 0
	s_add_i32 m0, s26, 0x0
	s_nop 0
	global_load_lds_dwordx4 v250, s[28:29]
	s_add_i32 m0, s26, 0x400
	s_nop 0
	global_load_lds_dwordx4 v251, s[28:29]
	s_add_u32 s30, s10, 0x40000
	s_cmp_eq_u32 s30, s21
	s_cbranch_scc1 .Lmpp_a_p_nok
	s_add_i32 m0, s36, 0x6000
	s_nop 0
	global_load_lds_dwordx4 v247, s[24:25]
	s_add_i32 m0, s36, 0x6400
	s_nop 0
	global_load_lds_dwordx4 v248, s[24:25]
	s_add_i32 m0, s36, 0x6800
	s_nop 0
	global_load_lds_dwordx4 v249, s[24:25]
	s_add_u32 s24, s24, 0x40000
	s_addc_u32 s25, s25, 0
.Lmpp_a_p_nok:
.Lmpp_a_pJ:
	ds_read_b64_tr_b16 v[82:83], v233 offset:16384
	ds_read_b64_tr_b16 v[84:85], v233 offset:18432
	ds_read_b64_tr_b16 v[86:87], v233 offset:20480
	ds_read_b64_tr_b16 v[88:89], v233 offset:22528
	ds_read_b64_tr_b16 v[90:91], v233 offset:24576
	ds_read_b64_tr_b16 v[92:93], v233 offset:26624
	ds_read_b64_tr_b16 v[94:95], v233 offset:28672
	ds_read_b64_tr_b16 v[96:97], v233 offset:30720
	s_nop 0
	s_waitcnt lgkmcnt(6)
	v_mfma_f32_32x32x16_bf16 v[2:17], v[78:81], v[82:85], v[2:17]
	ds_read_b64_tr_b16 v[82:83], v233 offset:16896
	ds_read_b64_tr_b16 v[84:85], v233 offset:18944
	s_waitcnt lgkmcnt(6)
	v_mfma_f32_32x32x16_bf16 v[2:17], v[74:77], v[86:89], v[2:17]
	ds_read_b64_tr_b16 v[86:87], v233 offset:20992
	ds_read_b64_tr_b16 v[88:89], v233 offset:23040
	s_waitcnt lgkmcnt(6)
	v_mfma_f32_32x32x16_bf16 v[2:17], v[70:73], v[90:93], v[2:17]
	ds_read_b64_tr_b16 v[90:91], v233 offset:25088
	ds_read_b64_tr_b16 v[92:93], v233 offset:27136
	s_waitcnt lgkmcnt(6)
	v_mfma_f32_32x32x16_bf16 v[2:17], v[66:69], v[94:97], v[2:17]
	ds_read_b64_tr_b16 v[94:95], v233 offset:29184
	ds_read_b64_tr_b16 v[96:97], v233 offset:31232
	s_waitcnt lgkmcnt(6)
	v_mfma_f32_32x32x16_bf16 v[18:33], v[78:81], v[82:85], v[18:33]
	ds_read_b64_tr_b16 v[82:83], v233 offset:17408
	ds_read_b64_tr_b16 v[84:85], v233 offset:19456
	s_waitcnt lgkmcnt(6)
	v_mfma_f32_32x32x16_bf16 v[18:33], v[74:77], v[86:89], v[18:33]
	ds_read_b64_tr_b16 v[86:87], v233 offset:21504
	ds_read_b64_tr_b16 v[88:89], v233 offset:23552
	s_waitcnt lgkmcnt(6)
	v_mfma_f32_32x32x16_bf16 v[18:33], v[70:73], v[90:93], v[18:33]
	ds_read_b64_tr_b16 v[90:91], v233 offset:25600
	ds_read_b64_tr_b16 v[92:93], v233 offset:27648
	s_waitcnt lgkmcnt(6)
	v_mfma_f32_32x32x16_bf16 v[18:33], v[66:69], v[94:97], v[18:33]
	ds_read_b64_tr_b16 v[94:95], v233 offset:29696
	ds_read_b64_tr_b16 v[96:97], v233 offset:31744
	s_waitcnt lgkmcnt(6)
	v_mfma_f32_32x32x16_bf16 v[34:49], v[78:81], v[82:85], v[34:49]
	ds_read_b64_tr_b16 v[82:83], v233 offset:17920
	ds_read_b64_tr_b16 v[84:85], v233 offset:19968
	s_waitcnt lgkmcnt(6)
	v_mfma_f32_32x32x16_bf16 v[34:49], v[74:77], v[86:89], v[34:49]
	ds_read_b64_tr_b16 v[86:87], v233 offset:22016
	ds_read_b64_tr_b16 v[88:89], v233 offset:24064
	s_waitcnt lgkmcnt(6)
	v_mfma_f32_32x32x16_bf16 v[34:49], v[70:73], v[90:93], v[34:49]
	ds_read_b64_tr_b16 v[90:91], v233 offset:26112
	ds_read_b64_tr_b16 v[92:93], v233 offset:28160
	s_waitcnt lgkmcnt(6)
	v_mfma_f32_32x32x16_bf16 v[34:49], v[66:69], v[94:97], v[34:49]
	ds_read_b64_tr_b16 v[94:95], v233 offset:30208
	ds_read_b64_tr_b16 v[96:97], v233 offset:32256
	s_waitcnt lgkmcnt(6)
	v_mfma_f32_32x32x16_bf16 v[50:65], v[78:81], v[82:85], v[50:65]
	s_waitcnt lgkmcnt(4)
	v_mfma_f32_32x32x16_bf16 v[50:65], v[74:77], v[86:89], v[50:65]
	s_add_u32 s10, s10, 0x40000
	s_addc_u32 s11, s11, 0
	s_add_i32 s22, s22, 1
	s_cmp_eq_u32 s21, s10
	s_waitcnt lgkmcnt(2)
	v_mfma_f32_32x32x16_bf16 v[50:65], v[70:73], v[90:93], v[50:65]
	s_waitcnt lgkmcnt(0)
	v_mfma_f32_32x32x16_bf16 v[50:65], v[66:69], v[94:97], v[50:65]
	v_mov_b32_e32 v234, v191
.Lmu_b120:
	ds_read_b128 v[66:69], v146 offset:24576
	ds_read_b128 v[70:73], v146 offset:36864
	ds_read_b128 v[236:239], v147 offset:24576
	ds_read_b128 v[240:243], v147 offset:36864
	s_waitcnt lgkmcnt(3)
	v_mfma_f32_32x32x16_bf16 v[82:97], v[66:69], v[134:137], 0
	s_waitcnt lgkmcnt(2)
	v_mfma_f32_32x32x16_bf16 v[66:81], v[70:73], v[134:137], 0
	ds_read_b128 v[148:151], v163 offset:24576
	ds_read_b128 v[152:155], v163 offset:36864
	s_waitcnt lgkmcnt(3)
	v_mfma_f32_32x32x16_bf16 v[82:97], v[236:239], v[130:133], v[82:97]
	s_waitcnt lgkmcnt(2)
	v_mfma_f32_32x32x16_bf16 v[66:81], v[240:243], v[130:133], v[66:81]
	ds_read_b128 v[236:239], v164 offset:24576
	ds_read_b128 v[240:243], v164 offset:36864
	s_waitcnt lgkmcnt(3)
	v_mfma_f32_32x32x16_bf16 v[82:97], v[148:151], v[126:129], v[82:97]
	s_waitcnt lgkmcnt(2)
	v_mfma_f32_32x32x16_bf16 v[66:81], v[152:155], v[126:129], v[66:81]
	ds_read_b128 v[148:151], v165 offset:24576
	ds_read_b128 v[152:155], v165 offset:36864
	s_waitcnt lgkmcnt(3)
	v_mfma_f32_32x32x16_bf16 v[82:97], v[236:239], v[122:125], v[82:97]
	s_waitcnt lgkmcnt(2)
	v_mfma_f32_32x32x16_bf16 v[66:81], v[240:243], v[122:125], v[66:81]
	ds_read_b128 v[236:239], v156 offset:24576
	ds_read_b128 v[240:243], v156 offset:36864
	s_waitcnt lgkmcnt(3)
	v_mfma_f32_32x32x16_bf16 v[82:97], v[148:151], v[118:121], v[82:97]
	s_waitcnt lgkmcnt(2)
	v_mfma_f32_32x32x16_bf16 v[66:81], v[152:155], v[118:121], v[66:81]
	ds_read_b128 v[148:151], v157 offset:24576
	ds_read_b128 v[152:155], v157 offset:36864
	s_waitcnt lgkmcnt(3)
	v_mfma_f32_32x32x16_bf16 v[82:97], v[236:239], v[114:117], v[82:97]
	s_waitcnt lgkmcnt(2)
	v_mfma_f32_32x32x16_bf16 v[66:81], v[240:243], v[114:117], v[66:81]
	ds_read_b128 v[236:239], v158 offset:24576
	ds_read_b128 v[240:243], v158 offset:36864
	s_waitcnt lgkmcnt(3)
	v_mfma_f32_32x32x16_bf16 v[82:97], v[148:151], v[110:113], v[82:97]
	s_waitcnt lgkmcnt(2)
	v_mfma_f32_32x32x16_bf16 v[66:81], v[152:155], v[110:113], v[66:81]
	ds_read_b128 v[148:151], v159 offset:24576
	ds_read_b128 v[152:155], v159 offset:36864
	s_waitcnt lgkmcnt(3)
	v_mfma_f32_32x32x16_bf16 v[82:97], v[236:239], v[106:109], v[82:97]
	s_waitcnt lgkmcnt(2)
	v_mfma_f32_32x32x16_bf16 v[66:81], v[240:243], v[106:109], v[66:81]
	ds_read_b128 v[236:239], v160 offset:24576
	ds_read_b128 v[240:243], v160 offset:36864
	s_waitcnt lgkmcnt(3)
	v_mfma_f32_32x32x16_bf16 v[82:97], v[148:151], v[102:105], v[82:97]
	s_waitcnt lgkmcnt(2)
	v_mfma_f32_32x32x16_bf16 v[66:81], v[152:155], v[102:105], v[66:81]
	ds_read_b128 v[148:151], v161 offset:24576
	ds_read_b128 v[152:155], v161 offset:36864
	s_waitcnt lgkmcnt(3)
	v_mfma_f32_32x32x16_bf16 v[82:97], v[236:239], v[98:101], v[82:97]
	s_waitcnt lgkmcnt(2)
	v_mfma_f32_32x32x16_bf16 v[66:81], v[240:243], v[98:101], v[66:81]
	ds_read_b128 v[236:239], v162 offset:24576
	ds_read_b128 v[240:243], v162 offset:36864
	s_waitcnt lgkmcnt(3)
	v_mfma_f32_32x32x16_bf16 v[82:97], v[148:151], v[138:141], v[82:97]
	s_waitcnt lgkmcnt(2)
	v_mfma_f32_32x32x16_bf16 v[66:81], v[152:155], v[138:141], v[66:81]
	s_waitcnt lgkmcnt(1)
	v_mfma_f32_32x32x16_bf16 v[82:97], v[236:239], v[142:145], v[82:97]
	s_waitcnt lgkmcnt(0)
	v_mfma_f32_32x32x16_bf16 v[66:81], v[240:243], v[142:145], v[66:81]
	s_cmpk_ge_u32 s26, 0x2010
	s_cbranch_scc0 .Lmpp_b_sA
	s_waitcnt vmcnt(0)
	s_barrier
	s_mov_b32 s30, 0x13572468
	s_mov_b32 s30, 0x13572468
	s_sub_u32 s28, s24, 0x40000
	s_subb_u32 s29, s25, 0
	s_add_i32 m0, s26, 0x4000
	s_nop 0
	global_load_lds_dwordx4 v250, s[28:29]
	s_add_i32 m0, s26, 0x4400
	s_nop 0
	global_load_lds_dwordx4 v251, s[28:29]
	s_add_u32 s30, s10, 0x40000
	s_cmp_eq_u32 s30, s21
	s_cbranch_scc1 .Lmpp_b_s_nok
	s_add_i32 m0, s36, 0x0
	s_nop 0
	global_load_lds_dwordx4 v247, s[24:25]
	s_add_i32 m0, s36, 0x400
	s_nop 0
	global_load_lds_dwordx4 v248, s[24:25]
	s_add_i32 m0, s36, 0x800
	s_nop 0
	global_load_lds_dwordx4 v249, s[24:25]
	s_add_u32 s24, s24, 0x40000
	s_addc_u32 s25, s25, 0

.Lmu_b124:
	v_add_f32_e32 v191, v82, v83
	v_fmac_f32_e32 v191, v234, v235
	s_cmpk_ge_u32 s26, 0x2010
	s_cbranch_scc1 .Lmpp_b_pJ
	s_waitcnt vmcnt(0)
	s_barrier
	s_mov_b32 s30, 0x13572468
	s_mov_b32 s30, 0x13572468
	s_mov_b32 s30, 0x13572468
	s_mov_b32 s30, 0x13572468
	s_mov_b32 s30, 0x13572468
	s_mov_b32 s30, 0x13572468
	s_sub_u32 s28, s24, 0x40000
	s_subb_u32 s29, s25, 0
	s_add_i32 m0, s26, 0x4000
	s_nop 0
	global_load_lds_dwordx4 v250, s[28:29]
	s_add_i32 m0, s26, 0x4400
	s_nop 0
	global_load_lds_dwordx4 v251, s[28:29]
	s_add_u32 s30, s10, 0x40000
	s_cmp_eq_u32 s30, s21
	s_cbranch_scc1 .Lmpp_b_p_nok
	s_add_i32 m0, s36, 0x0
	s_nop 0
	global_load_lds_dwordx4 v247, s[24:25]
	s_add_i32 m0, s36, 0x400
	s_nop 0
	global_load_lds_dwordx4 v248, s[24:25]
	s_add_i32 m0, s36, 0x800
	s_nop 0
	global_load_lds_dwordx4 v249, s[24:25]
	s_add_u32 s24, s24, 0x40000
	s_addc_u32 s25, s25, 0
.Lmpp_b_p_nok:
.Lmpp_b_pJ:
	ds_read_b64_tr_b16 v[82:83], v233 offset:0
	ds_read_b64_tr_b16 v[84:85], v233 offset:2048
	ds_read_b64_tr_b16 v[86:87], v233 offset:4096
	ds_read_b64_tr_b16 v[88:89], v233 offset:6144
	ds_read_b64_tr_b16 v[90:91], v233 offset:8192
	ds_read_b64_tr_b16 v[92:93], v233 offset:10240
	ds_read_b64_tr_b16 v[94:95], v233 offset:12288
	ds_read_b64_tr_b16 v[96:97], v233 offset:14336
	s_nop 0
	s_waitcnt lgkmcnt(6)
	v_mfma_f32_32x32x16_bf16 v[2:17], v[78:81], v[82:85], v[2:17]
	ds_read_b64_tr_b16 v[82:83], v233 offset:512
	ds_read_b64_tr_b16 v[84:85], v233 offset:2560
	s_waitcnt lgkmcnt(6)
	v_mfma_f32_32x32x16_bf16 v[2:17], v[74:77], v[86:89], v[2:17]
	ds_read_b64_tr_b16 v[86:87], v233 offset:4608
	ds_read_b64_tr_b16 v[88:89], v233 offset:6656
	s_waitcnt lgkmcnt(6)
	v_mfma_f32_32x32x16_bf16 v[2:17], v[70:73], v[90:93], v[2:17]
	ds_read_b64_tr_b16 v[90:91], v233 offset:8704
	ds_read_b64_tr_b16 v[92:93], v233 offset:10752
	s_waitcnt lgkmcnt(6)
	v_mfma_f32_32x32x16_bf16 v[2:17], v[66:69], v[94:97], v[2:17]
	ds_read_b64_tr_b16 v[94:95], v233 offset:12800
	ds_read_b64_tr_b16 v[96:97], v233 offset:14848
	s_waitcnt lgkmcnt(6)
	v_mfma_f32_32x32x16_bf16 v[18:33], v[78:81], v[82:85], v[18:33]
	ds_read_b64_tr_b16 v[82:83], v233 offset:1024
	ds_read_b64_tr_b16 v[84:85], v233 offset:3072
	s_waitcnt lgkmcnt(6)
	v_mfma_f32_32x32x16_bf16 v[18:33], v[74:77], v[86:89], v[18:33]
	ds_read_b64_tr_b16 v[86:87], v233 offset:5120
	ds_read_b64_tr_b16 v[88:89], v233 offset:7168
	s_waitcnt lgkmcnt(6)
	v_mfma_f32_32x32x16_bf16 v[18:33], v[70:73], v[90:93], v[18:33]
	ds_read_b64_tr_b16 v[90:91], v233 offset:9216
	ds_read_b64_tr_b16 v[92:93], v233 offset:11264
	s_waitcnt lgkmcnt(6)
	v_mfma_f32_32x32x16_bf16 v[18:33], v[66:69], v[94:97], v[18:33]
	ds_read_b64_tr_b16 v[94:95], v233 offset:13312
	ds_read_b64_tr_b16 v[96:97], v233 offset:15360
	s_waitcnt lgkmcnt(6)
	v_mfma_f32_32x32x16_bf16 v[34:49], v[78:81], v[82:85], v[34:49]
	ds_read_b64_tr_b16 v[82:83], v233 offset:1536
	ds_read_b64_tr_b16 v[84:85], v233 offset:3584
	s_waitcnt lgkmcnt(6)
	v_mfma_f32_32x32x16_bf16 v[34:49], v[74:77], v[86:89], v[34:49]
	ds_read_b64_tr_b16 v[86:87], v233 offset:5632
	ds_read_b64_tr_b16 v[88:89], v233 offset:7680
	s_waitcnt lgkmcnt(6)
	v_mfma_f32_32x32x16_bf16 v[34:49], v[70:73], v[90:93], v[34:49]
	ds_read_b64_tr_b16 v[90:91], v233 offset:9728
	ds_read_b64_tr_b16 v[92:93], v233 offset:11776
	s_waitcnt lgkmcnt(6)
	v_mfma_f32_32x32x16_bf16 v[34:49], v[66:69], v[94:97], v[34:49]
	ds_read_b64_tr_b16 v[94:95], v233 offset:13824
	ds_read_b64_tr_b16 v[96:97], v233 offset:15872
	s_waitcnt lgkmcnt(6)
	v_mfma_f32_32x32x16_bf16 v[50:65], v[78:81], v[82:85], v[50:65]
	s_waitcnt lgkmcnt(4)
	v_mfma_f32_32x32x16_bf16 v[50:65], v[74:77], v[86:89], v[50:65]
	s_add_u32 s10, s10, 0x40000
	s_addc_u32 s11, s11, 0
	s_add_i32 s22, s22, 1
	s_cmp_eq_u32 s21, s10
	s_waitcnt lgkmcnt(2)
	v_mfma_f32_32x32x16_bf16 v[50:65], v[70:73], v[90:93], v[50:65]
	s_waitcnt lgkmcnt(0)
	v_mfma_f32_32x32x16_bf16 v[50:65], v[66:69], v[94:97], v[50:65]
	s_cbranch_scc1 .LBB0_126
	v_mov_b32_e32 v234, v191
	s_branch .Lmu_a120
.LBB0_126:
	s_mov_b32 s30, 0x13572468
	s_mov_b32 s30, 0x13572468
	s_mov_b32 s30, 0x13572468
	s_mov_b32 s30, 0x13572468
	s_mov_b32 s30, 0x13572468
	s_mov_b32 s30, 0x13572468
	s_mov_b32 s30, 0x13572468
	s_mov_b32 s30, 0x13572468
	s_mov_b32 s30, 0x13572468
	s_mov_b32 s30, 0x13572468
	s_mov_b32 s30, 0x13572468
	s_mov_b32 s30, 0x13572468
	s_mov_b32 s30, 0x13572468
	s_mov_b32 s30, 0x13572468
	s_mov_b32 s30, 0x13572468
	s_and_b32 s12, s22, 1
	s_mul_i32 s10, s12, 0x6000
	v_add_u32_e32 v150, s10, v203
	v_add_u32_e32 v70, v150, v220
	ds_read_b128 v[66:69], v70 offset:32768
	ds_read_b128 v[70:73], v70 offset:45056
	v_add_u32_e32 v146, v150, v221
	s_waitcnt lgkmcnt(1)
	v_mfma_f32_32x32x16_bf16 v[82:97], v[66:69], v[134:137], 0
	s_waitcnt lgkmcnt(0)
	v_mfma_f32_32x32x16_bf16 v[66:81], v[70:73], v[134:137], 0
	ds_read_b128 v[134:137], v146 offset:32768
	ds_read_b128 v[146:149], v146 offset:45056
	s_waitcnt lgkmcnt(1)
	v_mfma_f32_32x32x16_bf16 v[82:97], v[134:137], v[130:133], v[82:97]
	v_add_u32_e32 v134, v150, v222
	s_waitcnt lgkmcnt(0)
	v_mfma_f32_32x32x16_bf16 v[66:81], v[146:149], v[130:133], v[66:81]
	ds_read_b128 v[130:133], v134 offset:32768
	ds_read_b128 v[134:137], v134 offset:45056
	s_waitcnt lgkmcnt(1)
	v_mfma_f32_32x32x16_bf16 v[82:97], v[130:133], v[126:129], v[82:97]
	v_add_u32_e32 v130, v150, v223
	s_waitcnt lgkmcnt(0)
	v_mfma_f32_32x32x16_bf16 v[66:81], v[134:137], v[126:129], v[66:81]
	ds_read_b128 v[126:129], v130 offset:32768
	ds_read_b128 v[130:133], v130 offset:45056
	s_waitcnt lgkmcnt(1)
	v_mfma_f32_32x32x16_bf16 v[82:97], v[126:129], v[122:125], v[82:97]
	v_add_u32_e32 v126, v150, v224
	s_waitcnt lgkmcnt(0)
	v_mfma_f32_32x32x16_bf16 v[66:81], v[130:133], v[122:125], v[66:81]
	ds_read_b128 v[122:125], v126 offset:32768
	ds_read_b128 v[126:129], v126 offset:45056
	s_waitcnt lgkmcnt(1)
	v_mfma_f32_32x32x16_bf16 v[82:97], v[122:125], v[118:121], v[82:97]
	v_add_u32_e32 v122, v150, v225
	s_waitcnt lgkmcnt(0)
	v_mfma_f32_32x32x16_bf16 v[66:81], v[126:129], v[118:121], v[66:81]
	ds_read_b128 v[118:121], v122 offset:32768
	ds_read_b128 v[122:125], v122 offset:45056
	s_waitcnt lgkmcnt(1)
	v_mfma_f32_32x32x16_bf16 v[82:97], v[118:121], v[114:117], v[82:97]
	v_add_u32_e32 v118, v150, v226
	s_waitcnt lgkmcnt(0)
	v_mfma_f32_32x32x16_bf16 v[66:81], v[122:125], v[114:117], v[66:81]
	ds_read_b128 v[114:117], v118 offset:32768
	ds_read_b128 v[118:121], v118 offset:45056
	s_waitcnt lgkmcnt(1)
	v_mfma_f32_32x32x16_bf16 v[82:97], v[114:117], v[110:113], v[82:97]
	v_add_u32_e32 v114, v150, v227
	s_waitcnt lgkmcnt(0)
	v_mfma_f32_32x32x16_bf16 v[66:81], v[118:121], v[110:113], v[66:81]
	ds_read_b128 v[110:113], v114 offset:32768
	ds_read_b128 v[114:117], v114 offset:45056
	s_waitcnt lgkmcnt(1)
	v_mfma_f32_32x32x16_bf16 v[82:97], v[110:113], v[106:109], v[82:97]
	v_add_u32_e32 v110, v150, v228
	s_waitcnt lgkmcnt(0)
	v_mfma_f32_32x32x16_bf16 v[66:81], v[114:117], v[106:109], v[66:81]
	ds_read_b128 v[106:109], v110 offset:32768
	ds_read_b128 v[110:113], v110 offset:45056
	s_waitcnt lgkmcnt(1)
	v_mfma_f32_32x32x16_bf16 v[82:97], v[106:109], v[102:105], v[82:97]
	v_add_u32_e32 v106, v150, v229
	s_waitcnt lgkmcnt(0)
	v_mfma_f32_32x32x16_bf16 v[66:81], v[110:113], v[102:105], v[66:81]
	ds_read_b128 v[102:105], v106 offset:32768
	ds_read_b128 v[106:109], v106 offset:45056
	s_waitcnt lgkmcnt(1)
	v_mfma_f32_32x32x16_bf16 v[82:97], v[102:105], v[98:101], v[82:97]
	v_add_u32_e32 v102, v150, v230
	s_waitcnt lgkmcnt(0)
	v_mfma_f32_32x32x16_bf16 v[66:81], v[106:109], v[98:101], v[66:81]
	ds_read_b128 v[98:101], v102 offset:32768
	ds_read_b128 v[102:105], v102 offset:45056
	v_add_u32_e32 v106, v150, v231
	s_waitcnt lgkmcnt(1)
	v_mfma_f32_32x32x16_bf16 v[82:97], v[98:101], v[138:141], v[82:97]
	ds_read_b128 v[98:101], v106 offset:32768
	ds_read_b128 v[106:109], v106 offset:45056
	s_waitcnt lgkmcnt(1)
	v_mfma_f32_32x32x16_bf16 v[82:97], v[98:101], v[142:145], v[82:97]
	v_max_f32_e32 v100, v189, v189
	v_mfma_f32_32x32x16_bf16 v[66:81], v[102:105], v[138:141], v[66:81]
	s_nop 9
	v_max_f32_e32 v98, v83, v83
	v_max_f32_e32 v99, v82, v82
	v_max_f32_e32 v98, v99, v98
	v_max3_f32 v98, v98, v84, v85
	v_max3_f32 v98, v98, v86, v87
	v_max3_f32 v98, v98, v88, v89
	v_max3_f32 v98, v98, v90, v91
	s_waitcnt lgkmcnt(0)
	v_mfma_f32_32x32x16_bf16 v[66:81], v[106:109], v[142:145], v[66:81]
	v_max3_f32 v98, v98, v92, v93
	v_max3_f32 v98, v98, v94, v95
	v_max3_f32 v98, v98, v96, v97
	s_nop 8
	v_max3_f32 v98, v98, v66, v67
	v_max3_f32 v98, v98, v68, v69
	v_max3_f32 v98, v98, v70, v71
	v_max3_f32 v98, v98, v72, v73
	v_max3_f32 v98, v98, v74, v75
	v_max3_f32 v98, v98, v76, v77
	v_max3_f32 v98, v98, v78, v79
	v_max3_f32 v98, v98, v80, v81
	v_mov_b32_e32 v99, v98
	s_nop 1
	v_permlane32_swap_b32_e32 v98, v99
	v_max_f32_e32 v99, v99, v99
	v_max_f32_e32 v98, v98, v98
	v_max_f32_e32 v98, v98, v99
	v_sub_f32_e32 v99, v98, v189
	v_cmp_ge_f32_e32 vcc, s56, v99
	s_cmp_eq_u64 vcc, exec
	v_max_f32_e32 v100, v100, v98
	s_cselect_b64 vcc, -1, 0
	v_cndmask_b32_e32 v99, v100, v189, vcc
	v_mul_f32_e32 v99, 0xbdd53b94, v99
	v_fmamk_f32 v82, v82, 0x3dd53b94, v99
	v_fmamk_f32 v83, v83, 0x3dd53b94, v99
	v_fmamk_f32 v84, v84, 0x3dd53b94, v99
	v_fmamk_f32 v85, v85, 0x3dd53b94, v99
	v_fmamk_f32 v86, v86, 0x3dd53b94, v99
	v_fmamk_f32 v87, v87, 0x3dd53b94, v99
	v_fmamk_f32 v88, v88, 0x3dd53b94, v99
	v_fmamk_f32 v89, v89, 0x3dd53b94, v99
	v_fmamk_f32 v90, v90, 0x3dd53b94, v99
	v_fmamk_f32 v91, v91, 0x3dd53b94, v99
	v_fmamk_f32 v92, v92, 0x3dd53b94, v99
	v_fmamk_f32 v93, v93, 0x3dd53b94, v99
	v_fmamk_f32 v94, v94, 0x3dd53b94, v99
	v_fmamk_f32 v95, v95, 0x3dd53b94, v99
	v_fmamk_f32 v96, v96, 0x3dd53b94, v99
	v_fmamk_f32 v97, v97, 0x3dd53b94, v99
	v_fmamk_f32 v66, v66, 0x3dd53b94, v99
	v_fmamk_f32 v67, v67, 0x3dd53b94, v99
	v_fmamk_f32 v68, v68, 0x3dd53b94, v99
	v_fmamk_f32 v69, v69, 0x3dd53b94, v99
	v_fmamk_f32 v70, v70, 0x3dd53b94, v99
	v_fmamk_f32 v71, v71, 0x3dd53b94, v99
	v_fmamk_f32 v72, v72, 0x3dd53b94, v99
	v_fmamk_f32 v73, v73, 0x3dd53b94, v99
	v_fmamk_f32 v74, v74, 0x3dd53b94, v99
	v_fmamk_f32 v75, v75, 0x3dd53b94, v99
	v_fmamk_f32 v76, v76, 0x3dd53b94, v99
	v_fmamk_f32 v77, v77, 0x3dd53b94, v99
	v_fmamk_f32 v78, v78, 0x3dd53b94, v99
	v_fmamk_f32 v79, v79, 0x3dd53b94, v99
	v_fmamk_f32 v80, v80, 0x3dd53b94, v99
	v_fmac_f32_e32 v99, 0x3dd53b94, v81
	v_exp_f32_e32 v81, v82
	v_sub_f32_e32 v98, v189, v100
	v_exp_f32_e32 v100, v83
	v_exp_f32_e32 v84, v84
	v_exp_f32_e32 v85, v85
	v_exp_f32_e32 v86, v86
	v_exp_f32_e32 v101, v70
	v_add_f32_e32 v70, 0, v81
	v_exp_f32_e32 v87, v87
	v_add_f32_e32 v70, v100, v70
	v_exp_f32_e32 v88, v88
	v_add_f32_e32 v70, v84, v70
	v_exp_f32_e32 v89, v89
	v_add_f32_e32 v70, v85, v70
	v_exp_f32_e32 v90, v90
	v_add_f32_e32 v70, v86, v70
	v_exp_f32_e32 v91, v91
	v_add_f32_e32 v70, v87, v70
	v_exp_f32_e32 v92, v92
	v_add_f32_e32 v70, v88, v70
	v_exp_f32_e32 v93, v93
	v_add_f32_e32 v70, v89, v70
	v_exp_f32_e32 v94, v94
	v_add_f32_e32 v70, v90, v70
	v_exp_f32_e32 v95, v95
	v_add_f32_e32 v70, v91, v70
	v_exp_f32_e32 v96, v96
	v_add_f32_e32 v70, v92, v70
	v_exp_f32_e32 v97, v97
	v_add_f32_e32 v70, v93, v70
	v_exp_f32_e32 v66, v66
	v_add_f32_e32 v70, v94, v70
	v_exp_f32_e32 v67, v67
	v_add_f32_e32 v70, v95, v70
	v_exp_f32_e32 v68, v68
	v_add_f32_e32 v70, v96, v70
	v_exp_f32_e32 v69, v69
	v_add_f32_e32 v70, v97, v70
	v_add_f32_e32 v70, v66, v70
	v_exp_f32_e32 v102, v71
	v_add_f32_e32 v70, v67, v70
	v_exp_f32_e32 v103, v72
	v_add_f32_e32 v70, v68, v70
	v_exp_f32_e32 v73, v73
	v_add_f32_e32 v70, v69, v70
	v_exp_f32_e32 v104, v74
	v_add_f32_e32 v70, v101, v70
	v_exp_f32_e32 v105, v75
	v_add_f32_e32 v70, v102, v70
	v_exp_f32_e32 v106, v76
	v_add_f32_e32 v70, v103, v70
	v_exp_f32_e32 v107, v77
	v_add_f32_e32 v70, v73, v70
	v_exp_f32_e32 v108, v78
	v_add_f32_e32 v70, v104, v70
	v_exp_f32_e32 v109, v79
	v_add_f32_e32 v70, v105, v70
	v_exp_f32_e32 v110, v80
	v_add_f32_e32 v70, v106, v70
	v_mul_f32_e32 v98, 0x3dd53b94, v98
	v_exp_f32_e32 v99, v99
	v_add_f32_e32 v70, v107, v70
	v_exp_f32_e32 v98, v98
	v_add_f32_e32 v70, v108, v70
	v_add_f32_e32 v70, v109, v70
	v_add_f32_e32 v70, v110, v70
	v_add_f32_e32 v82, v99, v70
	v_cndmask_b32_e64 v98, v98, 1.0, vcc
	v_mov_b32_e32 v83, v82
	s_nop 1
	v_permlane32_swap_b32_e32 v82, v83
	v_cmp_gt_f32_e32 vcc, 1.0, v98
	v_cvt_pk_bf16_f32 v78, v81, v100
	v_cvt_pk_bf16_f32 v79, v84, v85
	v_cvt_pk_bf16_f32 v80, v86, v87
	v_cvt_pk_bf16_f32 v81, v88, v89
	v_cvt_pk_bf16_f32 v74, v90, v91
	v_cvt_pk_bf16_f32 v75, v92, v93
	v_cvt_pk_bf16_f32 v76, v94, v95
	v_cvt_pk_bf16_f32 v77, v96, v97
	v_cvt_pk_bf16_f32 v70, v66, v67
	v_cvt_pk_bf16_f32 v71, v68, v69
	v_cvt_pk_bf16_f32 v72, v101, v102
	v_cvt_pk_bf16_f32 v73, v103, v73
	v_cvt_pk_bf16_f32 v66, v104, v105
	v_cvt_pk_bf16_f32 v67, v106, v107
	v_cvt_pk_bf16_f32 v68, v108, v109
	v_cvt_pk_bf16_f32 v69, v110, v99
	s_cbranch_vccz .LBB0_130
	s_and_saveexec_b64 s[10:11], s[4:5]
	ds_write_b32 v232, v98 offset:128
	s_or_b64 exec, exec, s[10:11]
	s_waitcnt lgkmcnt(0)
	v_add_u32_e32 v96, v196, v202
	ds_read_b128 v[84:87], v96 offset:224
	ds_read_b128 v[88:91], v96 offset:192
	ds_read_b128 v[92:95], v96 offset:160
	ds_read_b128 v[100:103], v96 offset:128
	s_waitcnt lgkmcnt(3)
	v_pk_mul_f32 v[14:15], v[14:15], v[84:85]
	s_waitcnt lgkmcnt(2)
	v_pk_mul_f32 v[10:11], v[10:11], v[88:89]
	s_waitcnt lgkmcnt(1)
	v_pk_mul_f32 v[6:7], v[6:7], v[92:93]
	v_pk_mul_f32 v[16:17], v[16:17], v[86:87]
	v_pk_mul_f32 v[12:13], v[12:13], v[90:91]
	v_pk_mul_f32 v[8:9], v[8:9], v[94:95]
	s_waitcnt lgkmcnt(0)
	v_pk_mul_f32 v[4:5], v[4:5], v[102:103]
	v_pk_mul_f32 v[2:3], v[2:3], v[100:101]
	v_pk_mul_f32 v[30:31], v[30:31], v[84:85]
	v_pk_mul_f32 v[26:27], v[26:27], v[88:89]
	v_pk_mul_f32 v[22:23], v[22:23], v[92:93]
	v_pk_mul_f32 v[32:33], v[32:33], v[86:87]
	v_pk_mul_f32 v[28:29], v[28:29], v[90:91]
	v_pk_mul_f32 v[24:25], v[24:25], v[94:95]
	v_pk_mul_f32 v[20:21], v[20:21], v[102:103]
	v_pk_mul_f32 v[18:19], v[18:19], v[100:101]
	v_pk_mul_f32 v[46:47], v[46:47], v[84:85]
	v_pk_mul_f32 v[42:43], v[42:43], v[88:89]
	v_pk_mul_f32 v[38:39], v[38:39], v[92:93]
	v_pk_mul_f32 v[48:49], v[48:49], v[86:87]
	v_pk_mul_f32 v[44:45], v[44:45], v[90:91]
	v_pk_mul_f32 v[40:41], v[40:41], v[94:95]
	v_pk_mul_f32 v[36:37], v[36:37], v[102:103]
	v_pk_mul_f32 v[34:35], v[34:35], v[100:101]
	v_pk_mul_f32 v[62:63], v[62:63], v[84:85]
	v_pk_mul_f32 v[58:59], v[58:59], v[88:89]
	v_pk_mul_f32 v[54:55], v[54:55], v[92:93]
	v_pk_mul_f32 v[64:65], v[64:65], v[86:87]
	v_pk_mul_f32 v[60:61], v[60:61], v[90:91]
	v_pk_mul_f32 v[56:57], v[56:57], v[94:95]
	v_pk_mul_f32 v[52:53], v[52:53], v[102:103]
	v_pk_mul_f32 v[50:51], v[50:51], v[100:101]
.LBB0_130:
	s_lshl_b64 s[8:9], s[8:9], 12
	s_add_u32 s8, s98, s8
	s_addc_u32 s9, s99, s9
	s_lshl_b32 s10, s20, 8
	s_add_u32 s8, s8, s10
	s_addc_u32 s9, s9, 0
	v_add_f32_e32 v82, v82, v83
	s_add_u32 s8, s8, 0x4600680
	v_fmac_f32_e32 v82, v191, v98
	s_addc_u32 s9, s9, 0
	s_waitcnt vmcnt(0)
	s_barrier
	v_lshl_add_u32 v83, s12, 14, v233
	ds_read_b64_tr_b16 v[84:85], v83 offset:0
	ds_read_b64_tr_b16 v[86:87], v83 offset:0x800
	ds_read_b64_tr_b16 v[88:89], v83 offset:0x1000
	ds_read_b64_tr_b16 v[90:91], v83 offset:0x1800
	ds_read_b64_tr_b16 v[92:93], v83 offset:0x2000
	ds_read_b64_tr_b16 v[94:95], v83 offset:0x2800
	ds_read_b64_tr_b16 v[96:97], v83 offset:0x3000
	ds_read_b64_tr_b16 v[98:99], v83 offset:0x3800
	s_waitcnt lgkmcnt(0)
	s_nop 0
	v_mfma_f32_32x32x16_bf16 v[2:17], v[78:81], v[84:87], v[2:17]
	ds_read_b64_tr_b16 v[84:85], v83 offset:0x200
	ds_read_b64_tr_b16 v[86:87], v83 offset:0xa00
	v_mfma_f32_32x32x16_bf16 v[2:17], v[74:77], v[88:91], v[2:17]
	ds_read_b64_tr_b16 v[88:89], v83 offset:0x1200
	ds_read_b64_tr_b16 v[90:91], v83 offset:0x1a00
	v_mfma_f32_32x32x16_bf16 v[2:17], v[70:73], v[92:95], v[2:17]
	ds_read_b64_tr_b16 v[92:93], v83 offset:0x2200
	ds_read_b64_tr_b16 v[94:95], v83 offset:0x2a00
	v_mfma_f32_32x32x16_bf16 v[2:17], v[66:69], v[96:99], v[2:17]
	ds_read_b64_tr_b16 v[96:97], v83 offset:0x3200
	ds_read_b64_tr_b16 v[98:99], v83 offset:0x3a00
	s_waitcnt lgkmcnt(0)
	v_mfma_f32_32x32x16_bf16 v[18:33], v[78:81], v[84:87], v[18:33]
	ds_read_b64_tr_b16 v[84:85], v83 offset:0x400
	ds_read_b64_tr_b16 v[86:87], v83 offset:0xc00
	v_mfma_f32_32x32x16_bf16 v[18:33], v[74:77], v[88:91], v[18:33]
	ds_read_b64_tr_b16 v[88:89], v83 offset:0x1400
	ds_read_b64_tr_b16 v[90:91], v83 offset:0x1c00
	v_mfma_f32_32x32x16_bf16 v[18:33], v[70:73], v[92:95], v[18:33]
	ds_read_b64_tr_b16 v[92:93], v83 offset:0x2400
	ds_read_b64_tr_b16 v[94:95], v83 offset:0x2c00
	v_mfma_f32_32x32x16_bf16 v[18:33], v[66:69], v[96:99], v[18:33]
	ds_read_b64_tr_b16 v[96:97], v83 offset:0x3400
	ds_read_b64_tr_b16 v[98:99], v83 offset:0x3c00
	s_waitcnt lgkmcnt(0)
	v_mfma_f32_32x32x16_bf16 v[34:49], v[78:81], v[84:87], v[34:49]
	ds_read_b64_tr_b16 v[84:85], v83 offset:0x600
	ds_read_b64_tr_b16 v[86:87], v83 offset:0xe00
	v_mfma_f32_32x32x16_bf16 v[34:49], v[74:77], v[88:91], v[34:49]
	ds_read_b64_tr_b16 v[88:89], v83 offset:0x1600
	ds_read_b64_tr_b16 v[90:91], v83 offset:0x1e00
	v_mfma_f32_32x32x16_bf16 v[34:49], v[70:73], v[92:95], v[34:49]
	ds_read_b64_tr_b16 v[92:93], v83 offset:0x2600
	ds_read_b64_tr_b16 v[94:95], v83 offset:0x2e00
	v_mfma_f32_32x32x16_bf16 v[34:49], v[66:69], v[96:99], v[34:49]
	ds_read_b64_tr_b16 v[96:97], v83 offset:0x3600
	ds_read_b64_tr_b16 v[98:99], v83 offset:0x3e00
	s_waitcnt lgkmcnt(0)
	v_mfma_f32_32x32x16_bf16 v[50:65], v[78:81], v[84:87], v[50:65]
	s_and_b64 vcc, exec, s[6:7]
	s_barrier
	v_mfma_f32_32x32x16_bf16 v[50:65], v[74:77], v[88:91], v[50:65]
	v_mfma_f32_32x32x16_bf16 v[50:65], v[70:73], v[92:95], v[50:65]
	v_mfma_f32_32x32x16_bf16 v[50:65], v[66:69], v[96:99], v[50:65]
	s_cbranch_vccz .LBB0_134
	s_and_saveexec_b64 s[10:11], s[4:5]
	ds_write_b32 v232, v82
	s_or_b64 exec, exec, s[10:11]
	s_waitcnt lgkmcnt(0)
	v_add_u32_e32 v191, v196, v202
	ds_read_b128 v[130:133], v191
	ds_read_b128 v[134:137], v191 offset:32
	ds_read_b128 v[138:141], v191 offset:64
	ds_read_b128 v[142:145], v191 offset:96
	v_add3_u32 v189, v180, v182, v190
	s_mov_b32 s12, s8
	s_mov_b32 s13, s9
	global_load_ushort v66, v189, s[12:13] offset:0
	global_load_ushort v67, v189, s[12:13] offset:64
	global_load_ushort v68, v189, s[12:13] offset:128
	global_load_ushort v69, v189, s[12:13] offset:192
	s_add_u32 s12, s12, 0x1000
	s_addc_u32 s13, s13, 0
	global_load_ushort v70, v189, s[12:13] offset:0
	global_load_ushort v71, v189, s[12:13] offset:64
	global_load_ushort v72, v189, s[12:13] offset:128
	global_load_ushort v73, v189, s[12:13] offset:192
	s_add_u32 s12, s12, 0x1000
	s_addc_u32 s13, s13, 0
	global_load_ushort v74, v189, s[12:13] offset:0
	global_load_ushort v75, v189, s[12:13] offset:64
	global_load_ushort v76, v189, s[12:13] offset:128
	global_load_ushort v77, v189, s[12:13] offset:192
	s_add_u32 s12, s12, 0x1000
	s_addc_u32 s13, s13, 0
	global_load_ushort v78, v189, s[12:13] offset:0
	global_load_ushort v79, v189, s[12:13] offset:64
	global_load_ushort v80, v189, s[12:13] offset:128
	global_load_ushort v81, v189, s[12:13] offset:192
	s_add_u32 s12, s12, 0x5000
	s_addc_u32 s13, s13, 0
	global_load_ushort v82, v189, s[12:13] offset:0
	global_load_ushort v83, v189, s[12:13] offset:64
	global_load_ushort v84, v189, s[12:13] offset:128
	global_load_ushort v85, v189, s[12:13] offset:192
	s_add_u32 s12, s12, 0x1000
	s_addc_u32 s13, s13, 0
	global_load_ushort v86, v189, s[12:13] offset:0
	global_load_ushort v87, v189, s[12:13] offset:64
	global_load_ushort v88, v189, s[12:13] offset:128
	global_load_ushort v89, v189, s[12:13] offset:192
	s_add_u32 s12, s12, 0x1000
	s_addc_u32 s13, s13, 0
	global_load_ushort v90, v189, s[12:13] offset:0
	global_load_ushort v91, v189, s[12:13] offset:64
	global_load_ushort v92, v189, s[12:13] offset:128
	global_load_ushort v93, v189, s[12:13] offset:192
	s_add_u32 s12, s12, 0x1000
	s_addc_u32 s13, s13, 0
	global_load_ushort v94, v189, s[12:13] offset:0
	global_load_ushort v95, v189, s[12:13] offset:64
	global_load_ushort v96, v189, s[12:13] offset:128
	global_load_ushort v97, v189, s[12:13] offset:192
	s_add_u32 s12, s12, 0x5000
	s_addc_u32 s13, s13, 0
	global_load_ushort v98, v189, s[12:13] offset:0
	global_load_ushort v99, v189, s[12:13] offset:64
	global_load_ushort v100, v189, s[12:13] offset:128
	global_load_ushort v101, v189, s[12:13] offset:192
	s_add_u32 s12, s12, 0x1000
	s_addc_u32 s13, s13, 0
	global_load_ushort v102, v189, s[12:13] offset:0
	global_load_ushort v103, v189, s[12:13] offset:64
	global_load_ushort v104, v189, s[12:13] offset:128
	global_load_ushort v105, v189, s[12:13] offset:192
	s_add_u32 s12, s12, 0x1000
	s_addc_u32 s13, s13, 0
	global_load_ushort v106, v189, s[12:13] offset:0
	global_load_ushort v107, v189, s[12:13] offset:64
	global_load_ushort v108, v189, s[12:13] offset:128
	global_load_ushort v109, v189, s[12:13] offset:192
	s_add_u32 s12, s12, 0x1000
	s_addc_u32 s13, s13, 0
	global_load_ushort v110, v189, s[12:13] offset:0
	global_load_ushort v111, v189, s[12:13] offset:64
	global_load_ushort v112, v189, s[12:13] offset:128
	global_load_ushort v113, v189, s[12:13] offset:192
	s_add_u32 s12, s12, 0x5000
	s_addc_u32 s13, s13, 0
	global_load_ushort v114, v189, s[12:13] offset:0
	global_load_ushort v115, v189, s[12:13] offset:64
	global_load_ushort v116, v189, s[12:13] offset:128
	global_load_ushort v117, v189, s[12:13] offset:192
	s_add_u32 s12, s12, 0x1000
	s_addc_u32 s13, s13, 0
	global_load_ushort v118, v189, s[12:13] offset:0
	global_load_ushort v119, v189, s[12:13] offset:64
	global_load_ushort v120, v189, s[12:13] offset:128
	global_load_ushort v121, v189, s[12:13] offset:192
	s_add_u32 s12, s12, 0x1000
	s_addc_u32 s13, s13, 0
	global_load_ushort v122, v189, s[12:13] offset:0
	global_load_ushort v123, v189, s[12:13] offset:64
	global_load_ushort v124, v189, s[12:13] offset:128
	global_load_ushort v125, v189, s[12:13] offset:192
	s_add_u32 s12, s12, 0x1000
	s_addc_u32 s13, s13, 0
	global_load_ushort v126, v189, s[12:13] offset:0
	global_load_ushort v127, v189, s[12:13] offset:64
	global_load_ushort v128, v189, s[12:13] offset:128
	global_load_ushort v129, v189, s[12:13] offset:192
	s_waitcnt lgkmcnt(0)
	v_rcp_f32_e32 v146, v130
	v_rcp_f32_e32 v147, v131
	v_rcp_f32_e32 v148, v132
	v_rcp_f32_e32 v149, v133
	v_rcp_f32_e32 v150, v134
	v_rcp_f32_e32 v151, v135
	v_rcp_f32_e32 v152, v136
	v_rcp_f32_e32 v153, v137
	v_rcp_f32_e32 v154, v138
	v_rcp_f32_e32 v155, v139
	v_rcp_f32_e32 v156, v140
	v_rcp_f32_e32 v157, v141
	v_rcp_f32_e32 v158, v142
	v_rcp_f32_e32 v159, v143
	v_rcp_f32_e32 v160, v144
	v_rcp_f32_e32 v161, v145
	s_waitcnt vmcnt(62)
	v_lshlrev_b32_e32 v66, 16, v66
	v_lshlrev_b32_e32 v67, 16, v67
	v_mul_f32_e32 v162, 0xbfb8aa3b, v66
	v_mul_f32_e32 v163, 0xbfb8aa3b, v67
	v_exp_f32_e32 v162, v162
	v_exp_f32_e32 v163, v163
	v_mul_f32_e32 v164, v2, v146
	v_mul_f32_e32 v165, v18, v146
	v_add_f32_e32 v162, 1.0, v162
	v_add_f32_e32 v163, 1.0, v163
	v_rcp_f32_e32 v162, v162
	v_rcp_f32_e32 v163, v163
	s_nop 0
	v_mul_f32_e32 v66, v162, v66
	v_mul_f32_e32 v67, v163, v67
	v_mul_f32_e32 v66, v164, v66
	v_mul_f32_e32 v67, v165, v67
	v_cvt_pk_bf16_f32 v66, v66, v66
	v_cvt_pk_bf16_f32 v67, v67, v67
	s_waitcnt vmcnt(60)
	v_lshlrev_b32_e32 v68, 16, v68
	v_lshlrev_b32_e32 v69, 16, v69
	v_mul_f32_e32 v162, 0xbfb8aa3b, v68
	v_mul_f32_e32 v163, 0xbfb8aa3b, v69
	v_exp_f32_e32 v162, v162
	v_exp_f32_e32 v163, v163
	v_mul_f32_e32 v164, v34, v146
	v_mul_f32_e32 v165, v50, v146
	v_add_f32_e32 v162, 1.0, v162
	v_add_f32_e32 v163, 1.0, v163
	v_rcp_f32_e32 v162, v162
	v_rcp_f32_e32 v163, v163
	s_nop 0
	v_mul_f32_e32 v68, v162, v68
	v_mul_f32_e32 v69, v163, v69
	v_mul_f32_e32 v68, v164, v68
	v_mul_f32_e32 v69, v165, v69
	v_cvt_pk_bf16_f32 v68, v68, v68
	v_cvt_pk_bf16_f32 v69, v69, v69
	s_waitcnt vmcnt(58)
	v_lshlrev_b32_e32 v70, 16, v70
	v_lshlrev_b32_e32 v71, 16, v71
	v_mul_f32_e32 v162, 0xbfb8aa3b, v70
	v_mul_f32_e32 v163, 0xbfb8aa3b, v71
	v_exp_f32_e32 v162, v162
	v_exp_f32_e32 v163, v163
	v_mul_f32_e32 v164, v3, v147
	v_mul_f32_e32 v165, v19, v147
	v_add_f32_e32 v162, 1.0, v162
	v_add_f32_e32 v163, 1.0, v163
	v_rcp_f32_e32 v162, v162
	v_rcp_f32_e32 v163, v163
	s_nop 0
	v_mul_f32_e32 v70, v162, v70
	v_mul_f32_e32 v71, v163, v71
	v_mul_f32_e32 v70, v164, v70
	v_mul_f32_e32 v71, v165, v71
	v_cvt_pk_bf16_f32 v70, v70, v70
	v_cvt_pk_bf16_f32 v71, v71, v71
	s_waitcnt vmcnt(56)
	v_lshlrev_b32_e32 v72, 16, v72
	v_lshlrev_b32_e32 v73, 16, v73
	v_mul_f32_e32 v162, 0xbfb8aa3b, v72
	v_mul_f32_e32 v163, 0xbfb8aa3b, v73
	v_exp_f32_e32 v162, v162
	v_exp_f32_e32 v163, v163
	v_mul_f32_e32 v164, v35, v147
	v_mul_f32_e32 v165, v51, v147
	v_add_f32_e32 v162, 1.0, v162
	v_add_f32_e32 v163, 1.0, v163
	v_rcp_f32_e32 v162, v162
	v_rcp_f32_e32 v163, v163
	s_nop 0
	v_mul_f32_e32 v72, v162, v72
	v_mul_f32_e32 v73, v163, v73
	v_mul_f32_e32 v72, v164, v72
	v_mul_f32_e32 v73, v165, v73
	v_cvt_pk_bf16_f32 v72, v72, v72
	v_cvt_pk_bf16_f32 v73, v73, v73
	s_waitcnt vmcnt(54)
	v_lshlrev_b32_e32 v74, 16, v74
	v_lshlrev_b32_e32 v75, 16, v75
	v_mul_f32_e32 v162, 0xbfb8aa3b, v74
	v_mul_f32_e32 v163, 0xbfb8aa3b, v75
	v_exp_f32_e32 v162, v162
	v_exp_f32_e32 v163, v163
	v_mul_f32_e32 v164, v4, v148
	v_mul_f32_e32 v165, v20, v148
	v_add_f32_e32 v162, 1.0, v162
	v_add_f32_e32 v163, 1.0, v163
	v_rcp_f32_e32 v162, v162
	v_rcp_f32_e32 v163, v163
	s_nop 0
	v_mul_f32_e32 v74, v162, v74
	v_mul_f32_e32 v75, v163, v75
	v_mul_f32_e32 v74, v164, v74
	v_mul_f32_e32 v75, v165, v75
	v_cvt_pk_bf16_f32 v74, v74, v74
	v_cvt_pk_bf16_f32 v75, v75, v75
	s_waitcnt vmcnt(52)
	v_lshlrev_b32_e32 v76, 16, v76
	v_lshlrev_b32_e32 v77, 16, v77
	v_mul_f32_e32 v162, 0xbfb8aa3b, v76
	v_mul_f32_e32 v163, 0xbfb8aa3b, v77
	v_exp_f32_e32 v162, v162
	v_exp_f32_e32 v163, v163
	v_mul_f32_e32 v164, v36, v148
	v_mul_f32_e32 v165, v52, v148
	v_add_f32_e32 v162, 1.0, v162
	v_add_f32_e32 v163, 1.0, v163
	v_rcp_f32_e32 v162, v162
	v_rcp_f32_e32 v163, v163
	s_nop 0
	v_mul_f32_e32 v76, v162, v76
	v_mul_f32_e32 v77, v163, v77
	v_mul_f32_e32 v76, v164, v76
	v_mul_f32_e32 v77, v165, v77
	v_cvt_pk_bf16_f32 v76, v76, v76
	v_cvt_pk_bf16_f32 v77, v77, v77
	s_waitcnt vmcnt(50)
	v_lshlrev_b32_e32 v78, 16, v78
	v_lshlrev_b32_e32 v79, 16, v79
	v_mul_f32_e32 v162, 0xbfb8aa3b, v78
	v_mul_f32_e32 v163, 0xbfb8aa3b, v79
	v_exp_f32_e32 v162, v162
	v_exp_f32_e32 v163, v163
	v_mul_f32_e32 v164, v5, v149
	v_mul_f32_e32 v165, v21, v149
	v_add_f32_e32 v162, 1.0, v162
	v_add_f32_e32 v163, 1.0, v163
	v_rcp_f32_e32 v162, v162
	v_rcp_f32_e32 v163, v163
	s_nop 0
	v_mul_f32_e32 v78, v162, v78
	v_mul_f32_e32 v79, v163, v79
	v_mul_f32_e32 v78, v164, v78
	v_mul_f32_e32 v79, v165, v79
	v_cvt_pk_bf16_f32 v78, v78, v78
	v_cvt_pk_bf16_f32 v79, v79, v79
	s_waitcnt vmcnt(48)
	v_lshlrev_b32_e32 v80, 16, v80
	v_lshlrev_b32_e32 v81, 16, v81
	v_mul_f32_e32 v162, 0xbfb8aa3b, v80
	v_mul_f32_e32 v163, 0xbfb8aa3b, v81
	v_exp_f32_e32 v162, v162
	v_exp_f32_e32 v163, v163
	v_mul_f32_e32 v164, v37, v149
	v_mul_f32_e32 v165, v53, v149
	v_add_f32_e32 v162, 1.0, v162
	v_add_f32_e32 v163, 1.0, v163
	v_rcp_f32_e32 v162, v162
	v_rcp_f32_e32 v163, v163
	s_nop 0
	v_mul_f32_e32 v80, v162, v80
	v_mul_f32_e32 v81, v163, v81
	v_mul_f32_e32 v80, v164, v80
	v_mul_f32_e32 v81, v165, v81
	v_cvt_pk_bf16_f32 v80, v80, v80
	v_cvt_pk_bf16_f32 v81, v81, v81
	s_waitcnt vmcnt(46)
	v_lshlrev_b32_e32 v82, 16, v82
	v_lshlrev_b32_e32 v83, 16, v83
	v_mul_f32_e32 v162, 0xbfb8aa3b, v82
	v_mul_f32_e32 v163, 0xbfb8aa3b, v83
	v_exp_f32_e32 v162, v162
	v_exp_f32_e32 v163, v163
	v_mul_f32_e32 v164, v6, v150
	v_mul_f32_e32 v165, v22, v150
	v_add_f32_e32 v162, 1.0, v162
	v_add_f32_e32 v163, 1.0, v163
	v_rcp_f32_e32 v162, v162
	v_rcp_f32_e32 v163, v163
	s_nop 0
	v_mul_f32_e32 v82, v162, v82
	v_mul_f32_e32 v83, v163, v83
	v_mul_f32_e32 v82, v164, v82
	v_mul_f32_e32 v83, v165, v83
	v_cvt_pk_bf16_f32 v82, v82, v82
	v_cvt_pk_bf16_f32 v83, v83, v83
	s_waitcnt vmcnt(44)
	v_lshlrev_b32_e32 v84, 16, v84
	v_lshlrev_b32_e32 v85, 16, v85
	v_mul_f32_e32 v162, 0xbfb8aa3b, v84
	v_mul_f32_e32 v163, 0xbfb8aa3b, v85
	v_exp_f32_e32 v162, v162
	v_exp_f32_e32 v163, v163
	v_mul_f32_e32 v164, v38, v150
	v_mul_f32_e32 v165, v54, v150
	v_add_f32_e32 v162, 1.0, v162
	v_add_f32_e32 v163, 1.0, v163
	v_rcp_f32_e32 v162, v162
	v_rcp_f32_e32 v163, v163
	s_nop 0
	v_mul_f32_e32 v84, v162, v84
	v_mul_f32_e32 v85, v163, v85
	v_mul_f32_e32 v84, v164, v84
	v_mul_f32_e32 v85, v165, v85
	v_cvt_pk_bf16_f32 v84, v84, v84
	v_cvt_pk_bf16_f32 v85, v85, v85
	s_waitcnt vmcnt(42)
	v_lshlrev_b32_e32 v86, 16, v86
	v_lshlrev_b32_e32 v87, 16, v87
	v_mul_f32_e32 v162, 0xbfb8aa3b, v86
	v_mul_f32_e32 v163, 0xbfb8aa3b, v87
	v_exp_f32_e32 v162, v162
	v_exp_f32_e32 v163, v163
	v_mul_f32_e32 v164, v7, v151
	v_mul_f32_e32 v165, v23, v151
	v_add_f32_e32 v162, 1.0, v162
	v_add_f32_e32 v163, 1.0, v163
	v_rcp_f32_e32 v162, v162
	v_rcp_f32_e32 v163, v163
	s_nop 0
	v_mul_f32_e32 v86, v162, v86
	v_mul_f32_e32 v87, v163, v87
	v_mul_f32_e32 v86, v164, v86
	v_mul_f32_e32 v87, v165, v87
	v_cvt_pk_bf16_f32 v86, v86, v86
	v_cvt_pk_bf16_f32 v87, v87, v87
	s_waitcnt vmcnt(40)
	v_lshlrev_b32_e32 v88, 16, v88
	v_lshlrev_b32_e32 v89, 16, v89
	v_mul_f32_e32 v162, 0xbfb8aa3b, v88
	v_mul_f32_e32 v163, 0xbfb8aa3b, v89
	v_exp_f32_e32 v162, v162
	v_exp_f32_e32 v163, v163
	v_mul_f32_e32 v164, v39, v151
	v_mul_f32_e32 v165, v55, v151
	v_add_f32_e32 v162, 1.0, v162
	v_add_f32_e32 v163, 1.0, v163
	v_rcp_f32_e32 v162, v162
	v_rcp_f32_e32 v163, v163
	s_nop 0
	v_mul_f32_e32 v88, v162, v88
	v_mul_f32_e32 v89, v163, v89
	v_mul_f32_e32 v88, v164, v88
	v_mul_f32_e32 v89, v165, v89
	v_cvt_pk_bf16_f32 v88, v88, v88
	v_cvt_pk_bf16_f32 v89, v89, v89
	s_waitcnt vmcnt(38)
	v_lshlrev_b32_e32 v90, 16, v90
	v_lshlrev_b32_e32 v91, 16, v91
	v_mul_f32_e32 v162, 0xbfb8aa3b, v90
	v_mul_f32_e32 v163, 0xbfb8aa3b, v91
	v_exp_f32_e32 v162, v162
	v_exp_f32_e32 v163, v163
	v_mul_f32_e32 v164, v8, v152
	v_mul_f32_e32 v165, v24, v152
	v_add_f32_e32 v162, 1.0, v162
	v_add_f32_e32 v163, 1.0, v163
	v_rcp_f32_e32 v162, v162
	v_rcp_f32_e32 v163, v163
	s_nop 0
	v_mul_f32_e32 v90, v162, v90
	v_mul_f32_e32 v91, v163, v91
	v_mul_f32_e32 v90, v164, v90
	v_mul_f32_e32 v91, v165, v91
	v_cvt_pk_bf16_f32 v90, v90, v90
	v_cvt_pk_bf16_f32 v91, v91, v91
	s_waitcnt vmcnt(36)
	v_lshlrev_b32_e32 v92, 16, v92
	v_lshlrev_b32_e32 v93, 16, v93
	v_mul_f32_e32 v162, 0xbfb8aa3b, v92
	v_mul_f32_e32 v163, 0xbfb8aa3b, v93
	v_exp_f32_e32 v162, v162
	v_exp_f32_e32 v163, v163
	v_mul_f32_e32 v164, v40, v152
	v_mul_f32_e32 v165, v56, v152
	v_add_f32_e32 v162, 1.0, v162
	v_add_f32_e32 v163, 1.0, v163
	v_rcp_f32_e32 v162, v162
	v_rcp_f32_e32 v163, v163
	s_nop 0
	v_mul_f32_e32 v92, v162, v92
	v_mul_f32_e32 v93, v163, v93
	v_mul_f32_e32 v92, v164, v92
	v_mul_f32_e32 v93, v165, v93
	v_cvt_pk_bf16_f32 v92, v92, v92
	v_cvt_pk_bf16_f32 v93, v93, v93
	s_waitcnt vmcnt(34)
	v_lshlrev_b32_e32 v94, 16, v94
	v_lshlrev_b32_e32 v95, 16, v95
	v_mul_f32_e32 v162, 0xbfb8aa3b, v94
	v_mul_f32_e32 v163, 0xbfb8aa3b, v95
	v_exp_f32_e32 v162, v162
	v_exp_f32_e32 v163, v163
	v_mul_f32_e32 v164, v9, v153
	v_mul_f32_e32 v165, v25, v153
	v_add_f32_e32 v162, 1.0, v162
	v_add_f32_e32 v163, 1.0, v163
	v_rcp_f32_e32 v162, v162
	v_rcp_f32_e32 v163, v163
	s_nop 0
	v_mul_f32_e32 v94, v162, v94
	v_mul_f32_e32 v95, v163, v95
	v_mul_f32_e32 v94, v164, v94
	v_mul_f32_e32 v95, v165, v95
	v_cvt_pk_bf16_f32 v94, v94, v94
	v_cvt_pk_bf16_f32 v95, v95, v95
	s_waitcnt vmcnt(32)
	v_lshlrev_b32_e32 v96, 16, v96
	v_lshlrev_b32_e32 v97, 16, v97
	v_mul_f32_e32 v162, 0xbfb8aa3b, v96
	v_mul_f32_e32 v163, 0xbfb8aa3b, v97
	v_exp_f32_e32 v162, v162
	v_exp_f32_e32 v163, v163
	v_mul_f32_e32 v164, v41, v153
	v_mul_f32_e32 v165, v57, v153
	v_add_f32_e32 v162, 1.0, v162
	v_add_f32_e32 v163, 1.0, v163
	v_rcp_f32_e32 v162, v162
	v_rcp_f32_e32 v163, v163
	s_nop 0
	v_mul_f32_e32 v96, v162, v96
	v_mul_f32_e32 v97, v163, v97
	v_mul_f32_e32 v96, v164, v96
	v_mul_f32_e32 v97, v165, v97
	v_cvt_pk_bf16_f32 v96, v96, v96
	v_cvt_pk_bf16_f32 v97, v97, v97
	s_waitcnt vmcnt(30)
	v_lshlrev_b32_e32 v98, 16, v98
	v_lshlrev_b32_e32 v99, 16, v99
	v_mul_f32_e32 v162, 0xbfb8aa3b, v98
	v_mul_f32_e32 v163, 0xbfb8aa3b, v99
	v_exp_f32_e32 v162, v162
	v_exp_f32_e32 v163, v163
	v_mul_f32_e32 v164, v10, v154
	v_mul_f32_e32 v165, v26, v154
	v_add_f32_e32 v162, 1.0, v162
	v_add_f32_e32 v163, 1.0, v163
	v_rcp_f32_e32 v162, v162
	v_rcp_f32_e32 v163, v163
	s_nop 0
	v_mul_f32_e32 v98, v162, v98
	v_mul_f32_e32 v99, v163, v99
	v_mul_f32_e32 v98, v164, v98
	v_mul_f32_e32 v99, v165, v99
	v_cvt_pk_bf16_f32 v98, v98, v98
	v_cvt_pk_bf16_f32 v99, v99, v99
	s_waitcnt vmcnt(28)
	v_lshlrev_b32_e32 v100, 16, v100
	v_lshlrev_b32_e32 v101, 16, v101
	v_mul_f32_e32 v162, 0xbfb8aa3b, v100
	v_mul_f32_e32 v163, 0xbfb8aa3b, v101
	v_exp_f32_e32 v162, v162
	v_exp_f32_e32 v163, v163
	v_mul_f32_e32 v164, v42, v154
	v_mul_f32_e32 v165, v58, v154
	v_add_f32_e32 v162, 1.0, v162
	v_add_f32_e32 v163, 1.0, v163
	v_rcp_f32_e32 v162, v162
	v_rcp_f32_e32 v163, v163
	s_nop 0
	v_mul_f32_e32 v100, v162, v100
	v_mul_f32_e32 v101, v163, v101
	v_mul_f32_e32 v100, v164, v100
	v_mul_f32_e32 v101, v165, v101
	v_cvt_pk_bf16_f32 v100, v100, v100
	v_cvt_pk_bf16_f32 v101, v101, v101
	s_waitcnt vmcnt(26)
	v_lshlrev_b32_e32 v102, 16, v102
	v_lshlrev_b32_e32 v103, 16, v103
	v_mul_f32_e32 v162, 0xbfb8aa3b, v102
	v_mul_f32_e32 v163, 0xbfb8aa3b, v103
	v_exp_f32_e32 v162, v162
	v_exp_f32_e32 v163, v163
	v_mul_f32_e32 v164, v11, v155
	v_mul_f32_e32 v165, v27, v155
	v_add_f32_e32 v162, 1.0, v162
	v_add_f32_e32 v163, 1.0, v163
	v_rcp_f32_e32 v162, v162
	v_rcp_f32_e32 v163, v163
	s_nop 0
	v_mul_f32_e32 v102, v162, v102
	v_mul_f32_e32 v103, v163, v103
	v_mul_f32_e32 v102, v164, v102
	v_mul_f32_e32 v103, v165, v103
	v_cvt_pk_bf16_f32 v102, v102, v102
	v_cvt_pk_bf16_f32 v103, v103, v103
	s_waitcnt vmcnt(24)
	v_lshlrev_b32_e32 v104, 16, v104
	v_lshlrev_b32_e32 v105, 16, v105
	v_mul_f32_e32 v162, 0xbfb8aa3b, v104
	v_mul_f32_e32 v163, 0xbfb8aa3b, v105
	v_exp_f32_e32 v162, v162
	v_exp_f32_e32 v163, v163
	v_mul_f32_e32 v164, v43, v155
	v_mul_f32_e32 v165, v59, v155
	v_add_f32_e32 v162, 1.0, v162
	v_add_f32_e32 v163, 1.0, v163
	v_rcp_f32_e32 v162, v162
	v_rcp_f32_e32 v163, v163
	s_nop 0
	v_mul_f32_e32 v104, v162, v104
	v_mul_f32_e32 v105, v163, v105
	v_mul_f32_e32 v104, v164, v104
	v_mul_f32_e32 v105, v165, v105
	v_cvt_pk_bf16_f32 v104, v104, v104
	v_cvt_pk_bf16_f32 v105, v105, v105
	s_waitcnt vmcnt(22)
	v_lshlrev_b32_e32 v106, 16, v106
	v_lshlrev_b32_e32 v107, 16, v107
	v_mul_f32_e32 v162, 0xbfb8aa3b, v106
	v_mul_f32_e32 v163, 0xbfb8aa3b, v107
	v_exp_f32_e32 v162, v162
	v_exp_f32_e32 v163, v163
	v_mul_f32_e32 v164, v12, v156
	v_mul_f32_e32 v165, v28, v156
	v_add_f32_e32 v162, 1.0, v162
	v_add_f32_e32 v163, 1.0, v163
	v_rcp_f32_e32 v162, v162
	v_rcp_f32_e32 v163, v163
	s_nop 0
	v_mul_f32_e32 v106, v162, v106
	v_mul_f32_e32 v107, v163, v107
	v_mul_f32_e32 v106, v164, v106
	v_mul_f32_e32 v107, v165, v107
	v_cvt_pk_bf16_f32 v106, v106, v106
	v_cvt_pk_bf16_f32 v107, v107, v107
	s_waitcnt vmcnt(20)
	v_lshlrev_b32_e32 v108, 16, v108
	v_lshlrev_b32_e32 v109, 16, v109
	v_mul_f32_e32 v162, 0xbfb8aa3b, v108
	v_mul_f32_e32 v163, 0xbfb8aa3b, v109
	v_exp_f32_e32 v162, v162
	v_exp_f32_e32 v163, v163
	v_mul_f32_e32 v164, v44, v156
	v_mul_f32_e32 v165, v60, v156
	v_add_f32_e32 v162, 1.0, v162
	v_add_f32_e32 v163, 1.0, v163
	v_rcp_f32_e32 v162, v162
	v_rcp_f32_e32 v163, v163
	s_nop 0
	v_mul_f32_e32 v108, v162, v108
	v_mul_f32_e32 v109, v163, v109
	v_mul_f32_e32 v108, v164, v108
	v_mul_f32_e32 v109, v165, v109
	v_cvt_pk_bf16_f32 v108, v108, v108
	v_cvt_pk_bf16_f32 v109, v109, v109
	s_waitcnt vmcnt(18)
	v_lshlrev_b32_e32 v110, 16, v110
	v_lshlrev_b32_e32 v111, 16, v111
	v_mul_f32_e32 v162, 0xbfb8aa3b, v110
	v_mul_f32_e32 v163, 0xbfb8aa3b, v111
	v_exp_f32_e32 v162, v162
	v_exp_f32_e32 v163, v163
	v_mul_f32_e32 v164, v13, v157
	v_mul_f32_e32 v165, v29, v157
	v_add_f32_e32 v162, 1.0, v162
	v_add_f32_e32 v163, 1.0, v163
	v_rcp_f32_e32 v162, v162
	v_rcp_f32_e32 v163, v163
	s_nop 0
	v_mul_f32_e32 v110, v162, v110
	v_mul_f32_e32 v111, v163, v111
	v_mul_f32_e32 v110, v164, v110
	v_mul_f32_e32 v111, v165, v111
	v_cvt_pk_bf16_f32 v110, v110, v110
	v_cvt_pk_bf16_f32 v111, v111, v111
	s_waitcnt vmcnt(16)
	v_lshlrev_b32_e32 v112, 16, v112
	v_lshlrev_b32_e32 v113, 16, v113
	v_mul_f32_e32 v162, 0xbfb8aa3b, v112
	v_mul_f32_e32 v163, 0xbfb8aa3b, v113
	v_exp_f32_e32 v162, v162
	v_exp_f32_e32 v163, v163
	v_mul_f32_e32 v164, v45, v157
	v_mul_f32_e32 v165, v61, v157
	v_add_f32_e32 v162, 1.0, v162
	v_add_f32_e32 v163, 1.0, v163
	v_rcp_f32_e32 v162, v162
	v_rcp_f32_e32 v163, v163
	s_nop 0
	v_mul_f32_e32 v112, v162, v112
	v_mul_f32_e32 v113, v163, v113
	v_mul_f32_e32 v112, v164, v112
	v_mul_f32_e32 v113, v165, v113
	v_cvt_pk_bf16_f32 v112, v112, v112
	v_cvt_pk_bf16_f32 v113, v113, v113
	s_waitcnt vmcnt(14)
	v_lshlrev_b32_e32 v114, 16, v114
	v_lshlrev_b32_e32 v115, 16, v115
	v_mul_f32_e32 v162, 0xbfb8aa3b, v114
	v_mul_f32_e32 v163, 0xbfb8aa3b, v115
	v_exp_f32_e32 v162, v162
	v_exp_f32_e32 v163, v163
	v_mul_f32_e32 v164, v14, v158
	v_mul_f32_e32 v165, v30, v158
	v_add_f32_e32 v162, 1.0, v162
	v_add_f32_e32 v163, 1.0, v163
	v_rcp_f32_e32 v162, v162
	v_rcp_f32_e32 v163, v163
	s_nop 0
	v_mul_f32_e32 v114, v162, v114
	v_mul_f32_e32 v115, v163, v115
	v_mul_f32_e32 v114, v164, v114
	v_mul_f32_e32 v115, v165, v115
	v_cvt_pk_bf16_f32 v114, v114, v114
	v_cvt_pk_bf16_f32 v115, v115, v115
	s_waitcnt vmcnt(12)
	v_lshlrev_b32_e32 v116, 16, v116
	v_lshlrev_b32_e32 v117, 16, v117
	v_mul_f32_e32 v162, 0xbfb8aa3b, v116
	v_mul_f32_e32 v163, 0xbfb8aa3b, v117
	v_exp_f32_e32 v162, v162
	v_exp_f32_e32 v163, v163
	v_mul_f32_e32 v164, v46, v158
	v_mul_f32_e32 v165, v62, v158
	v_add_f32_e32 v162, 1.0, v162
	v_add_f32_e32 v163, 1.0, v163
	v_rcp_f32_e32 v162, v162
	v_rcp_f32_e32 v163, v163
	s_nop 0
	v_mul_f32_e32 v116, v162, v116
	v_mul_f32_e32 v117, v163, v117
	v_mul_f32_e32 v116, v164, v116
	v_mul_f32_e32 v117, v165, v117
	v_cvt_pk_bf16_f32 v116, v116, v116
	v_cvt_pk_bf16_f32 v117, v117, v117
	s_waitcnt vmcnt(10)
	v_lshlrev_b32_e32 v118, 16, v118
	v_lshlrev_b32_e32 v119, 16, v119
	v_mul_f32_e32 v162, 0xbfb8aa3b, v118
	v_mul_f32_e32 v163, 0xbfb8aa3b, v119
	v_exp_f32_e32 v162, v162
	v_exp_f32_e32 v163, v163
	v_mul_f32_e32 v164, v15, v159
	v_mul_f32_e32 v165, v31, v159
	v_add_f32_e32 v162, 1.0, v162
	v_add_f32_e32 v163, 1.0, v163
	v_rcp_f32_e32 v162, v162
	v_rcp_f32_e32 v163, v163
	s_nop 0
	v_mul_f32_e32 v118, v162, v118
	v_mul_f32_e32 v119, v163, v119
	v_mul_f32_e32 v118, v164, v118
	v_mul_f32_e32 v119, v165, v119
	v_cvt_pk_bf16_f32 v118, v118, v118
	v_cvt_pk_bf16_f32 v119, v119, v119
	s_waitcnt vmcnt(8)
	v_lshlrev_b32_e32 v120, 16, v120
	v_lshlrev_b32_e32 v121, 16, v121
	v_mul_f32_e32 v162, 0xbfb8aa3b, v120
	v_mul_f32_e32 v163, 0xbfb8aa3b, v121
	v_exp_f32_e32 v162, v162
	v_exp_f32_e32 v163, v163
	v_mul_f32_e32 v164, v47, v159
	v_mul_f32_e32 v165, v63, v159
	v_add_f32_e32 v162, 1.0, v162
	v_add_f32_e32 v163, 1.0, v163
	v_rcp_f32_e32 v162, v162
	v_rcp_f32_e32 v163, v163
	s_nop 0
	v_mul_f32_e32 v120, v162, v120
	v_mul_f32_e32 v121, v163, v121
	v_mul_f32_e32 v120, v164, v120
	v_mul_f32_e32 v121, v165, v121
	v_cvt_pk_bf16_f32 v120, v120, v120
	v_cvt_pk_bf16_f32 v121, v121, v121
	s_waitcnt vmcnt(6)
	v_lshlrev_b32_e32 v122, 16, v122
	v_lshlrev_b32_e32 v123, 16, v123
	v_mul_f32_e32 v162, 0xbfb8aa3b, v122
	v_mul_f32_e32 v163, 0xbfb8aa3b, v123
	v_exp_f32_e32 v162, v162
	v_exp_f32_e32 v163, v163
	v_mul_f32_e32 v164, v16, v160
	v_mul_f32_e32 v165, v32, v160
	v_add_f32_e32 v162, 1.0, v162
	v_add_f32_e32 v163, 1.0, v163
	v_rcp_f32_e32 v162, v162
	v_rcp_f32_e32 v163, v163
	s_nop 0
	v_mul_f32_e32 v122, v162, v122
	v_mul_f32_e32 v123, v163, v123
	v_mul_f32_e32 v122, v164, v122
	v_mul_f32_e32 v123, v165, v123
	v_cvt_pk_bf16_f32 v122, v122, v122
	v_cvt_pk_bf16_f32 v123, v123, v123
	s_waitcnt vmcnt(4)
	v_lshlrev_b32_e32 v124, 16, v124
	v_lshlrev_b32_e32 v125, 16, v125
	v_mul_f32_e32 v162, 0xbfb8aa3b, v124
	v_mul_f32_e32 v163, 0xbfb8aa3b, v125
	v_exp_f32_e32 v162, v162
	v_exp_f32_e32 v163, v163
	v_mul_f32_e32 v164, v48, v160
	v_mul_f32_e32 v165, v64, v160
	v_add_f32_e32 v162, 1.0, v162
	v_add_f32_e32 v163, 1.0, v163
	v_rcp_f32_e32 v162, v162
	v_rcp_f32_e32 v163, v163
	s_nop 0
	v_mul_f32_e32 v124, v162, v124
	v_mul_f32_e32 v125, v163, v125
	v_mul_f32_e32 v124, v164, v124
	v_mul_f32_e32 v125, v165, v125
	v_cvt_pk_bf16_f32 v124, v124, v124
	v_cvt_pk_bf16_f32 v125, v125, v125
	s_waitcnt vmcnt(2)
	v_lshlrev_b32_e32 v126, 16, v126
	v_lshlrev_b32_e32 v127, 16, v127
	v_mul_f32_e32 v162, 0xbfb8aa3b, v126
	v_mul_f32_e32 v163, 0xbfb8aa3b, v127
	v_exp_f32_e32 v162, v162
	v_exp_f32_e32 v163, v163
	v_mul_f32_e32 v164, v17, v161
	v_mul_f32_e32 v165, v33, v161
	v_add_f32_e32 v162, 1.0, v162
	v_add_f32_e32 v163, 1.0, v163
	v_rcp_f32_e32 v162, v162
	v_rcp_f32_e32 v163, v163
	s_nop 0
	v_mul_f32_e32 v126, v162, v126
	v_mul_f32_e32 v127, v163, v127
	v_mul_f32_e32 v126, v164, v126
	v_mul_f32_e32 v127, v165, v127
	v_cvt_pk_bf16_f32 v126, v126, v126
	v_cvt_pk_bf16_f32 v127, v127, v127
	s_waitcnt vmcnt(0)
	v_lshlrev_b32_e32 v128, 16, v128
	v_lshlrev_b32_e32 v129, 16, v129
	v_mul_f32_e32 v162, 0xbfb8aa3b, v128
	v_mul_f32_e32 v163, 0xbfb8aa3b, v129
	v_exp_f32_e32 v162, v162
	v_exp_f32_e32 v163, v163
	v_mul_f32_e32 v164, v49, v161
	v_mul_f32_e32 v165, v65, v161
	v_add_f32_e32 v162, 1.0, v162
	v_add_f32_e32 v163, 1.0, v163
	v_rcp_f32_e32 v162, v162
	v_rcp_f32_e32 v163, v163
	s_nop 0
	v_mul_f32_e32 v128, v162, v128
	v_mul_f32_e32 v129, v163, v129
	v_mul_f32_e32 v128, v164, v128
	v_mul_f32_e32 v129, v165, v129
	v_cvt_pk_bf16_f32 v128, v128, v128
	v_cvt_pk_bf16_f32 v129, v129, v129
	s_mov_b32 s12, s8
	s_mov_b32 s13, s9
	global_store_short v189, v66, s[12:13] offset:0
	global_store_short v189, v67, s[12:13] offset:64
	global_store_short v189, v68, s[12:13] offset:128
	global_store_short v189, v69, s[12:13] offset:192
	s_add_u32 s12, s12, 0x1000
	s_addc_u32 s13, s13, 0
	global_store_short v189, v70, s[12:13] offset:0
	global_store_short v189, v71, s[12:13] offset:64
	global_store_short v189, v72, s[12:13] offset:128
	global_store_short v189, v73, s[12:13] offset:192
	s_add_u32 s12, s12, 0x1000
	s_addc_u32 s13, s13, 0
	global_store_short v189, v74, s[12:13] offset:0
	global_store_short v189, v75, s[12:13] offset:64
	global_store_short v189, v76, s[12:13] offset:128
	global_store_short v189, v77, s[12:13] offset:192
	s_add_u32 s12, s12, 0x1000
	s_addc_u32 s13, s13, 0
	global_store_short v189, v78, s[12:13] offset:0
	global_store_short v189, v79, s[12:13] offset:64
	global_store_short v189, v80, s[12:13] offset:128
	global_store_short v189, v81, s[12:13] offset:192
	s_add_u32 s12, s12, 0x5000
	s_addc_u32 s13, s13, 0
	global_store_short v189, v82, s[12:13] offset:0
	global_store_short v189, v83, s[12:13] offset:64
	global_store_short v189, v84, s[12:13] offset:128
	global_store_short v189, v85, s[12:13] offset:192
	s_add_u32 s12, s12, 0x1000
	s_addc_u32 s13, s13, 0
	global_store_short v189, v86, s[12:13] offset:0
	global_store_short v189, v87, s[12:13] offset:64
	global_store_short v189, v88, s[12:13] offset:128
	global_store_short v189, v89, s[12:13] offset:192
	s_add_u32 s12, s12, 0x1000
	s_addc_u32 s13, s13, 0
	global_store_short v189, v90, s[12:13] offset:0
	global_store_short v189, v91, s[12:13] offset:64
	global_store_short v189, v92, s[12:13] offset:128
	global_store_short v189, v93, s[12:13] offset:192
	s_add_u32 s12, s12, 0x1000
	s_addc_u32 s13, s13, 0
	global_store_short v189, v94, s[12:13] offset:0
	global_store_short v189, v95, s[12:13] offset:64
	global_store_short v189, v96, s[12:13] offset:128
	global_store_short v189, v97, s[12:13] offset:192
	s_add_u32 s12, s12, 0x5000
	s_addc_u32 s13, s13, 0
	global_store_short v189, v98, s[12:13] offset:0
	global_store_short v189, v99, s[12:13] offset:64
	global_store_short v189, v100, s[12:13] offset:128
	global_store_short v189, v101, s[12:13] offset:192
	s_add_u32 s12, s12, 0x1000
	s_addc_u32 s13, s13, 0
	global_store_short v189, v102, s[12:13] offset:0
	global_store_short v189, v103, s[12:13] offset:64
	global_store_short v189, v104, s[12:13] offset:128
	global_store_short v189, v105, s[12:13] offset:192
	s_add_u32 s12, s12, 0x1000
	s_addc_u32 s13, s13, 0
	global_store_short v189, v106, s[12:13] offset:0
	global_store_short v189, v107, s[12:13] offset:64
	global_store_short v189, v108, s[12:13] offset:128
	global_store_short v189, v109, s[12:13] offset:192
	s_add_u32 s12, s12, 0x1000
	s_addc_u32 s13, s13, 0
	global_store_short v189, v110, s[12:13] offset:0
	global_store_short v189, v111, s[12:13] offset:64
	global_store_short v189, v112, s[12:13] offset:128
	global_store_short v189, v113, s[12:13] offset:192
	s_add_u32 s12, s12, 0x5000
	s_addc_u32 s13, s13, 0
	global_store_short v189, v114, s[12:13] offset:0
	global_store_short v189, v115, s[12:13] offset:64
	global_store_short v189, v116, s[12:13] offset:128
	global_store_short v189, v117, s[12:13] offset:192
	s_add_u32 s12, s12, 0x1000
	s_addc_u32 s13, s13, 0
	global_store_short v189, v118, s[12:13] offset:0
	global_store_short v189, v119, s[12:13] offset:64
	global_store_short v189, v120, s[12:13] offset:128
	global_store_short v189, v121, s[12:13] offset:192
	s_add_u32 s12, s12, 0x1000
	s_addc_u32 s13, s13, 0
	global_store_short v189, v122, s[12:13] offset:0
	global_store_short v189, v123, s[12:13] offset:64
	global_store_short v189, v124, s[12:13] offset:128
	global_store_short v189, v125, s[12:13] offset:192
	s_add_u32 s12, s12, 0x1000
	s_addc_u32 s13, s13, 0
	global_store_short v189, v126, s[12:13] offset:0
	global_store_short v189, v127, s[12:13] offset:64
	global_store_short v189, v128, s[12:13] offset:128
	global_store_short v189, v129, s[12:13] offset:192
	s_branch .LBB0_109
